# v15 + loop-edge edits: attention back-edge bookkeeping moved into the PV phase's MFMA shadow; GEMM K-loop counter/pointer SALU block moved above the loop-back barrier (7 loops)
# baseline (speedup 1.0000x reference)
.LBB0_145:
	s_ashr_i32 s17, s16, 31
	s_lshl_b64 s[18:19], s[16:17], 19
	s_add_u32 s18, s36, s18
	s_addc_u32 s19, s37, s19
	s_and_b64 s[20:21], s[2:3], exec
	s_cselect_b32 s17, s19, s25
	s_cselect_b32 s50, s18, s24
	s_ashr_i32 s15, s14, 31
	s_lshl_b64 s[20:21], s[14:15], 19
	s_add_u32 s20, s34, s20
	s_addc_u32 s21, s35, s21
	s_and_b64 s[28:29], s[2:3], exec
	s_cselect_b32 s15, s21, s27
	s_cselect_b32 s51, s20, s26
	s_add_u32 s24, s24, 0x40080
	s_addc_u32 s25, s25, 0
	s_add_u32 s52, s26, 0x100
	v_mov_b32_e32 v0, 0
	s_addc_u32 s53, s27, 0
	s_mov_b32 s54, -2
	v_mov_b32_e32 v1, v0
	v_mov_b32_e32 v2, v0
	v_mov_b32_e32 v3, v0
	v_mov_b32_e32 v8, v0
	v_mov_b32_e32 v9, v0
	v_mov_b32_e32 v10, v0
	v_mov_b32_e32 v11, v0
	v_mov_b32_e32 v16, v0
	v_mov_b32_e32 v17, v0
	v_mov_b32_e32 v18, v0
	v_mov_b32_e32 v19, v0
	v_mov_b32_e32 v24, v0
	v_mov_b32_e32 v25, v0
	v_mov_b32_e32 v26, v0
	v_mov_b32_e32 v27, v0
	v_mov_b32_e32 v32, v0
	v_mov_b32_e32 v33, v0
	v_mov_b32_e32 v34, v0
	v_mov_b32_e32 v35, v0
	v_mov_b32_e32 v40, v0
	v_mov_b32_e32 v41, v0
	v_mov_b32_e32 v42, v0
	v_mov_b32_e32 v43, v0
	v_mov_b32_e32 v48, v0
	v_mov_b32_e32 v49, v0
	v_mov_b32_e32 v50, v0
	v_mov_b32_e32 v51, v0
	v_mov_b32_e32 v56, v0
	v_mov_b32_e32 v57, v0
	v_mov_b32_e32 v58, v0
	v_mov_b32_e32 v59, v0
	v_mov_b32_e32 v4, v0
	v_mov_b32_e32 v5, v0
	v_mov_b32_e32 v6, v0
	v_mov_b32_e32 v7, v0
	v_mov_b32_e32 v12, v0
	v_mov_b32_e32 v13, v0
	v_mov_b32_e32 v14, v0
	v_mov_b32_e32 v15, v0
	v_mov_b32_e32 v20, v0
	v_mov_b32_e32 v21, v0
	v_mov_b32_e32 v22, v0
	v_mov_b32_e32 v23, v0
	v_mov_b32_e32 v28, v0
	v_mov_b32_e32 v29, v0
	v_mov_b32_e32 v30, v0
	v_mov_b32_e32 v31, v0
	v_mov_b32_e32 v36, v0
	v_mov_b32_e32 v37, v0
	v_mov_b32_e32 v38, v0
	v_mov_b32_e32 v39, v0
	v_mov_b32_e32 v44, v0
	v_mov_b32_e32 v45, v0
	v_mov_b32_e32 v46, v0
	v_mov_b32_e32 v47, v0
	v_mov_b32_e32 v52, v0
	v_mov_b32_e32 v53, v0
	v_mov_b32_e32 v54, v0
	v_mov_b32_e32 v55, v0
	v_mov_b32_e32 v60, v0
	v_mov_b32_e32 v61, v0
	v_mov_b32_e32 v62, v0
	v_mov_b32_e32 v63, v0
	v_mov_b32_e32 v64, v0
	v_mov_b32_e32 v65, v0
	v_mov_b32_e32 v66, v0
	v_mov_b32_e32 v67, v0
	v_mov_b32_e32 v72, v0
	v_mov_b32_e32 v73, v0
	v_mov_b32_e32 v74, v0
	v_mov_b32_e32 v75, v0
	v_mov_b32_e32 v80, v0
	v_mov_b32_e32 v81, v0
	v_mov_b32_e32 v82, v0
	v_mov_b32_e32 v83, v0
	v_mov_b32_e32 v88, v0
	v_mov_b32_e32 v89, v0
	v_mov_b32_e32 v90, v0
	v_mov_b32_e32 v91, v0
	v_mov_b32_e32 v98, v0
	v_mov_b32_e32 v99, v0
	v_mov_b32_e32 v100, v0
	v_mov_b32_e32 v101, v0
	v_mov_b32_e32 v106, v0
	v_mov_b32_e32 v107, v0
	v_mov_b32_e32 v108, v0
	v_mov_b32_e32 v109, v0
	v_mov_b32_e32 v114, v0
	v_mov_b32_e32 v115, v0
	v_mov_b32_e32 v116, v0
	v_mov_b32_e32 v117, v0
	v_mov_b32_e32 v122, v0
	v_mov_b32_e32 v123, v0
	v_mov_b32_e32 v124, v0
	v_mov_b32_e32 v125, v0
	v_mov_b32_e32 v68, v0
	v_mov_b32_e32 v69, v0
	v_mov_b32_e32 v70, v0
	v_mov_b32_e32 v71, v0
	v_mov_b32_e32 v76, v0
	v_mov_b32_e32 v77, v0
	v_mov_b32_e32 v78, v0
	v_mov_b32_e32 v79, v0
	v_mov_b32_e32 v84, v0
	v_mov_b32_e32 v85, v0
	v_mov_b32_e32 v86, v0
	v_mov_b32_e32 v87, v0
	v_mov_b32_e32 v92, v0
	v_mov_b32_e32 v93, v0
	v_mov_b32_e32 v94, v0
	v_mov_b32_e32 v95, v0
	v_mov_b32_e32 v102, v0
	v_mov_b32_e32 v103, v0
	v_mov_b32_e32 v104, v0
	v_mov_b32_e32 v105, v0
	v_mov_b32_e32 v110, v0
	v_mov_b32_e32 v111, v0
	v_mov_b32_e32 v112, v0
	v_mov_b32_e32 v113, v0
	v_mov_b32_e32 v118, v0
	v_mov_b32_e32 v119, v0
	v_mov_b32_e32 v120, v0
	v_mov_b32_e32 v121, v0
	v_mov_b32_e32 v126, v0
	v_mov_b32_e32 v127, v0
	v_mov_b32_e32 v128, v0
	v_mov_b32_e32 v129, v0
	s_add_u32 s26, s24, 0xfffc0080
	s_addc_u32 s27, s25, -1
	s_add_i32 s55, 0, 0x10000
	s_cmp_eq_u32 s54, 12
	s_cselect_b32 s29, s17, s27
	s_cselect_b32 s28, s50, s26
	v_add_u32_e32 v140, s55, v143
	s_cselect_b32 s27, s15, s53
	s_cselect_b32 s26, s51, s52
	s_add_i32 s60, 0, 0x14000
	ds_read_b128 v[150:153], v140
	ds_read_b128 v[154:157], v140 offset:1024
	ds_read_b128 v[158:161], v140 offset:2048
	ds_read_b128 v[162:165], v140 offset:3072
	v_add_u32_e32 v140, s60, v143
	ds_read_b128 v[166:169], v140
	ds_read_b128 v[170:173], v140 offset:1024
	ds_read_b128 v[174:177], v140 offset:2048
	ds_read_b128 v[178:181], v140 offset:3072
	v_lshl_add_u64 v[140:141], s[24:25], 0, v[136:137]
	s_add_i32 m0, s40, 0xc000
	ds_read_b128 v[182:185], v148
	ds_read_b128 v[186:189], v148 offset:1024
	ds_read_b128 v[190:193], v148 offset:2048
	ds_read_b128 v[202:205], v148 offset:3072
	ds_read_b128 v[206:209], v148 offset:4096
	ds_read_b128 v[210:213], v148 offset:5120
	ds_read_b128 v[214:217], v148 offset:6144
	ds_read_b128 v[218:221], v148 offset:7168
	global_load_lds_dwordx4 v[140:141], off
	v_lshl_add_u64 v[140:141], s[24:25], 0, v[138:139]
	s_add_i32 m0, s40, 0xe000
	s_nop 0
	global_load_lds_dwordx4 v[140:141], off
	s_waitcnt lgkmcnt(0)
	s_barrier
	s_setprio 1
	s_waitcnt lgkmcnt(0)
	v_mfma_f32_16x16x32_bf16 v[126:129], v[150:153], v[182:185], v[126:129]
	v_mfma_f32_16x16x32_bf16 v[118:121], v[158:161], v[182:185], v[118:121]
	v_mfma_f32_16x16x32_bf16 v[110:113], v[150:153], v[190:193], v[110:113]
	v_mfma_f32_16x16x32_bf16 v[102:105], v[158:161], v[190:193], v[102:105]
	v_mfma_f32_16x16x32_bf16 v[92:95], v[150:153], v[206:209], v[92:95]
	v_mfma_f32_16x16x32_bf16 v[84:87], v[158:161], v[206:209], v[84:87]
	v_mfma_f32_16x16x32_bf16 v[76:79], v[150:153], v[214:217], v[76:79]
	v_mfma_f32_16x16x32_bf16 v[68:71], v[158:161], v[214:217], v[68:71]
	v_mfma_f32_16x16x32_bf16 v[126:129], v[154:157], v[186:189], v[126:129]
	v_mfma_f32_16x16x32_bf16 v[118:121], v[162:165], v[186:189], v[118:121]
	v_mfma_f32_16x16x32_bf16 v[110:113], v[154:157], v[202:205], v[110:113]
	v_mfma_f32_16x16x32_bf16 v[102:105], v[162:165], v[202:205], v[102:105]
	v_mfma_f32_16x16x32_bf16 v[92:95], v[154:157], v[210:213], v[92:95]
	v_mfma_f32_16x16x32_bf16 v[84:87], v[162:165], v[210:213], v[84:87]
	v_mfma_f32_16x16x32_bf16 v[76:79], v[154:157], v[218:221], v[76:79]
	v_mfma_f32_16x16x32_bf16 v[68:71], v[162:165], v[218:221], v[68:71]
	s_setprio 0
	s_setprio 1
	v_mfma_f32_16x16x32_bf16 v[122:125], v[166:169], v[182:185], v[122:125]
	v_mfma_f32_16x16x32_bf16 v[114:117], v[174:177], v[182:185], v[114:117]
	v_mfma_f32_16x16x32_bf16 v[106:109], v[166:169], v[190:193], v[106:109]
	v_mfma_f32_16x16x32_bf16 v[98:101], v[174:177], v[190:193], v[98:101]
	v_mfma_f32_16x16x32_bf16 v[88:91], v[166:169], v[206:209], v[88:91]
	v_mfma_f32_16x16x32_bf16 v[80:83], v[174:177], v[206:209], v[80:83]
	v_mfma_f32_16x16x32_bf16 v[72:75], v[166:169], v[214:217], v[72:75]
	v_mfma_f32_16x16x32_bf16 v[64:67], v[174:177], v[214:217], v[64:67]
	v_mfma_f32_16x16x32_bf16 v[122:125], v[170:173], v[186:189], v[122:125]
	v_mfma_f32_16x16x32_bf16 v[114:117], v[178:181], v[186:189], v[114:117]
	v_mfma_f32_16x16x32_bf16 v[106:109], v[170:173], v[202:205], v[106:109]
	v_mfma_f32_16x16x32_bf16 v[98:101], v[178:181], v[202:205], v[98:101]
	v_mfma_f32_16x16x32_bf16 v[88:91], v[170:173], v[210:213], v[88:91]
	v_mfma_f32_16x16x32_bf16 v[80:83], v[178:181], v[210:213], v[80:83]
	v_mfma_f32_16x16x32_bf16 v[72:75], v[170:173], v[218:221], v[72:75]
	v_mfma_f32_16x16x32_bf16 v[64:67], v[178:181], v[218:221], v[64:67]
	s_setprio 0
	s_barrier
	s_add_i32 s55, s55, s39
	v_lshl_add_u64 v[140:141], s[26:27], 0, v[96:97]
	s_mov_b32 m0, s55
	ds_read_b128 v[182:185], v148 offset:16384
	ds_read_b128 v[186:189], v148 offset:17408
	ds_read_b128 v[190:193], v148 offset:18432
	ds_read_b128 v[202:205], v148 offset:19456
	ds_read_b128 v[206:209], v148 offset:20480
	ds_read_b128 v[210:213], v148 offset:21504
	ds_read_b128 v[214:217], v148 offset:22528
	ds_read_b128 v[218:221], v148 offset:23552
	global_load_lds_dwordx4 v[140:141], off
	s_add_i32 m0, s55, 0x2000
	s_add_u32 s56, s26, 0x40000
	v_lshl_add_u64 v[194:195], s[26:27], 0, v[130:131]
	s_addc_u32 s57, s27, 0
	s_add_i32 s55, s60, s39
	global_load_lds_dwordx4 v[194:195], off
	v_lshl_add_u64 v[196:197], s[56:57], 0, v[96:97]
	s_mov_b32 m0, s55
	v_lshl_add_u64 v[198:199], s[28:29], 0, v[132:133]
	global_load_lds_dwordx4 v[196:197], off
	v_lshl_add_u64 v[196:197], s[56:57], 0, v[130:131]
	s_add_i32 m0, s55, 0x2000
	s_nop 0
	global_load_lds_dwordx4 v[196:197], off
	v_lshl_add_u64 v[196:197], s[28:29], 0, v[134:135]
	s_mov_b32 m0, s40
	s_nop 0
	global_load_lds_dwordx4 v[196:197], off
	s_mov_b32 m0, s41
	s_nop 0
	global_load_lds_dwordx4 v[198:199], off
	s_waitcnt lgkmcnt(0)
	s_barrier
	s_setprio 1
	s_waitcnt lgkmcnt(0)
	v_mfma_f32_16x16x32_bf16 v[60:63], v[150:153], v[182:185], v[60:63]
	v_mfma_f32_16x16x32_bf16 v[52:55], v[158:161], v[182:185], v[52:55]
	v_mfma_f32_16x16x32_bf16 v[44:47], v[150:153], v[190:193], v[44:47]
	v_mfma_f32_16x16x32_bf16 v[36:39], v[158:161], v[190:193], v[36:39]
	v_mfma_f32_16x16x32_bf16 v[28:31], v[150:153], v[206:209], v[28:31]
	v_mfma_f32_16x16x32_bf16 v[20:23], v[158:161], v[206:209], v[20:23]
	v_mfma_f32_16x16x32_bf16 v[12:15], v[150:153], v[214:217], v[12:15]
	v_mfma_f32_16x16x32_bf16 v[4:7], v[158:161], v[214:217], v[4:7]
	v_mfma_f32_16x16x32_bf16 v[60:63], v[154:157], v[186:189], v[60:63]
	v_mfma_f32_16x16x32_bf16 v[52:55], v[162:165], v[186:189], v[52:55]
	v_mfma_f32_16x16x32_bf16 v[44:47], v[154:157], v[202:205], v[44:47]
	v_mfma_f32_16x16x32_bf16 v[36:39], v[162:165], v[202:205], v[36:39]
	v_mfma_f32_16x16x32_bf16 v[28:31], v[154:157], v[210:213], v[28:31]
	v_mfma_f32_16x16x32_bf16 v[20:23], v[162:165], v[210:213], v[20:23]
	v_mfma_f32_16x16x32_bf16 v[12:15], v[154:157], v[218:221], v[12:15]
	v_mfma_f32_16x16x32_bf16 v[4:7], v[162:165], v[218:221], v[4:7]
	s_setprio 0
	s_setprio 1
	v_mfma_f32_16x16x32_bf16 v[56:59], v[166:169], v[182:185], v[56:59]
	v_mfma_f32_16x16x32_bf16 v[48:51], v[174:177], v[182:185], v[48:51]
	v_mfma_f32_16x16x32_bf16 v[40:43], v[166:169], v[190:193], v[40:43]
	v_mfma_f32_16x16x32_bf16 v[32:35], v[174:177], v[190:193], v[32:35]
	v_mfma_f32_16x16x32_bf16 v[24:27], v[166:169], v[206:209], v[24:27]
	v_mfma_f32_16x16x32_bf16 v[16:19], v[174:177], v[206:209], v[16:19]
	v_mfma_f32_16x16x32_bf16 v[8:11], v[166:169], v[214:217], v[8:11]
	v_mfma_f32_16x16x32_bf16 v[0:3], v[174:177], v[214:217], v[0:3]
	v_mfma_f32_16x16x32_bf16 v[56:59], v[170:173], v[186:189], v[56:59]
	v_mfma_f32_16x16x32_bf16 v[48:51], v[178:181], v[186:189], v[48:51]
	v_mfma_f32_16x16x32_bf16 v[40:43], v[170:173], v[202:205], v[40:43]
	v_mfma_f32_16x16x32_bf16 v[32:35], v[178:181], v[202:205], v[32:35]
	v_mfma_f32_16x16x32_bf16 v[24:27], v[170:173], v[210:213], v[24:27]
	v_mfma_f32_16x16x32_bf16 v[16:19], v[178:181], v[210:213], v[16:19]
	v_mfma_f32_16x16x32_bf16 v[8:11], v[170:173], v[218:221], v[8:11]
	v_mfma_f32_16x16x32_bf16 v[0:3], v[178:181], v[218:221], v[0:3]
	s_setprio 0
	s_barrier
	s_add_i32 s55, 0, 0x18000
	v_add_u32_e32 v149, s55, v143
	s_add_i32 s56, 0, 0x1c000
	ds_read_b128 v[150:153], v149
	ds_read_b128 v[154:157], v149 offset:1024
	ds_read_b128 v[158:161], v149 offset:2048
	ds_read_b128 v[162:165], v149 offset:3072
	v_add_u32_e32 v149, s56, v143
	ds_read_b128 v[166:169], v149
	ds_read_b128 v[170:173], v149 offset:1024
	ds_read_b128 v[174:177], v149 offset:2048
	ds_read_b128 v[178:181], v149 offset:3072
	s_add_u32 s28, s28, 0x40000
	s_addc_u32 s29, s29, 0
	s_mov_b32 m0, s42
	v_lshl_add_u64 v[200:201], s[28:29], 0, v[134:135]
	ds_read_b128 v[182:185], v148 offset:32768
	ds_read_b128 v[186:189], v148 offset:33792
	ds_read_b128 v[190:193], v148 offset:34816
	ds_read_b128 v[202:205], v148 offset:35840
	ds_read_b128 v[206:209], v148 offset:36864
	ds_read_b128 v[210:213], v148 offset:37888
	ds_read_b128 v[214:217], v148 offset:38912
	ds_read_b128 v[218:221], v148 offset:39936
	global_load_lds_dwordx4 v[200:201], off
	v_lshl_add_u64 v[200:201], s[28:29], 0, v[132:133]
	s_mov_b32 m0, s43
	s_nop 0
	global_load_lds_dwordx4 v[200:201], off
	s_waitcnt vmcnt(8)
	s_waitcnt lgkmcnt(0)
	s_barrier
	s_setprio 1
	s_waitcnt lgkmcnt(0)
	v_mfma_f32_16x16x32_bf16 v[126:129], v[150:153], v[182:185], v[126:129]
	v_mfma_f32_16x16x32_bf16 v[118:121], v[158:161], v[182:185], v[118:121]
	v_mfma_f32_16x16x32_bf16 v[110:113], v[150:153], v[190:193], v[110:113]
	v_mfma_f32_16x16x32_bf16 v[102:105], v[158:161], v[190:193], v[102:105]
	v_mfma_f32_16x16x32_bf16 v[92:95], v[150:153], v[206:209], v[92:95]
	v_mfma_f32_16x16x32_bf16 v[84:87], v[158:161], v[206:209], v[84:87]
	v_mfma_f32_16x16x32_bf16 v[76:79], v[150:153], v[214:217], v[76:79]
	v_mfma_f32_16x16x32_bf16 v[68:71], v[158:161], v[214:217], v[68:71]
	v_mfma_f32_16x16x32_bf16 v[126:129], v[154:157], v[186:189], v[126:129]
	v_mfma_f32_16x16x32_bf16 v[118:121], v[162:165], v[186:189], v[118:121]
	v_mfma_f32_16x16x32_bf16 v[110:113], v[154:157], v[202:205], v[110:113]
	v_mfma_f32_16x16x32_bf16 v[102:105], v[162:165], v[202:205], v[102:105]
	v_mfma_f32_16x16x32_bf16 v[92:95], v[154:157], v[210:213], v[92:95]
	v_mfma_f32_16x16x32_bf16 v[84:87], v[162:165], v[210:213], v[84:87]
	v_mfma_f32_16x16x32_bf16 v[76:79], v[154:157], v[218:221], v[76:79]
	v_mfma_f32_16x16x32_bf16 v[68:71], v[162:165], v[218:221], v[68:71]
	s_setprio 0
	s_setprio 1
	v_mfma_f32_16x16x32_bf16 v[122:125], v[166:169], v[182:185], v[122:125]
	v_mfma_f32_16x16x32_bf16 v[114:117], v[174:177], v[182:185], v[114:117]
	v_mfma_f32_16x16x32_bf16 v[106:109], v[166:169], v[190:193], v[106:109]
	v_mfma_f32_16x16x32_bf16 v[98:101], v[174:177], v[190:193], v[98:101]
	v_mfma_f32_16x16x32_bf16 v[88:91], v[166:169], v[206:209], v[88:91]
	v_mfma_f32_16x16x32_bf16 v[80:83], v[174:177], v[206:209], v[80:83]
	v_mfma_f32_16x16x32_bf16 v[72:75], v[166:169], v[214:217], v[72:75]
	v_mfma_f32_16x16x32_bf16 v[64:67], v[174:177], v[214:217], v[64:67]
	v_mfma_f32_16x16x32_bf16 v[122:125], v[170:173], v[186:189], v[122:125]
	v_mfma_f32_16x16x32_bf16 v[114:117], v[178:181], v[186:189], v[114:117]
	v_mfma_f32_16x16x32_bf16 v[106:109], v[170:173], v[202:205], v[106:109]
	v_mfma_f32_16x16x32_bf16 v[98:101], v[178:181], v[202:205], v[98:101]
	v_mfma_f32_16x16x32_bf16 v[88:91], v[170:173], v[210:213], v[88:91]
	v_mfma_f32_16x16x32_bf16 v[80:83], v[178:181], v[210:213], v[80:83]
	v_mfma_f32_16x16x32_bf16 v[72:75], v[170:173], v[218:221], v[72:75]
	v_mfma_f32_16x16x32_bf16 v[64:67], v[178:181], v[218:221], v[64:67]
	s_setprio 0
	s_barrier
	s_add_i32 s28, s55, s39
	v_lshl_add_u64 v[140:141], v[140:141], 0, s[64:65]
	s_mov_b32 m0, s28
	ds_read_b128 v[182:185], v148 offset:49152
	ds_read_b128 v[186:189], v148 offset:50176
	ds_read_b128 v[190:193], v148 offset:51200
	ds_read_b128 v[202:205], v148 offset:52224
	ds_read_b128 v[206:209], v148 offset:53248
	ds_read_b128 v[210:213], v148 offset:54272
	ds_read_b128 v[214:217], v148 offset:55296
	ds_read_b128 v[218:221], v148 offset:56320
	global_load_lds_dwordx4 v[140:141], off
	s_add_i32 m0, s28, 0x2000
	s_add_u32 s26, s26, 0x40080
	v_lshl_add_u64 v[140:141], v[194:195], 0, s[64:65]
	s_addc_u32 s27, s27, 0
	s_add_i32 s28, s56, s39
	global_load_lds_dwordx4 v[140:141], off
	v_lshl_add_u64 v[140:141], s[26:27], 0, v[96:97]
	s_mov_b32 m0, s28
	s_nop 0
	global_load_lds_dwordx4 v[140:141], off
	v_lshl_add_u64 v[140:141], s[26:27], 0, v[130:131]
	s_add_i32 m0, s28, 0x2000
	s_nop 0
	global_load_lds_dwordx4 v[140:141], off
	v_lshl_add_u64 v[140:141], v[196:197], 0, s[64:65]
	s_mov_b32 m0, s44
	s_nop 0
	global_load_lds_dwordx4 v[140:141], off
	v_lshl_add_u64 v[140:141], v[198:199], 0, s[64:65]
	s_mov_b32 m0, s45
	s_nop 0
	global_load_lds_dwordx4 v[140:141], off
	s_waitcnt vmcnt(8)
	s_waitcnt lgkmcnt(0)
	s_barrier
	s_setprio 1
	s_waitcnt lgkmcnt(0)
	v_mfma_f32_16x16x32_bf16 v[60:63], v[150:153], v[182:185], v[60:63]
	v_mfma_f32_16x16x32_bf16 v[52:55], v[158:161], v[182:185], v[52:55]
	v_mfma_f32_16x16x32_bf16 v[44:47], v[150:153], v[190:193], v[44:47]
	v_mfma_f32_16x16x32_bf16 v[36:39], v[158:161], v[190:193], v[36:39]
	v_mfma_f32_16x16x32_bf16 v[28:31], v[150:153], v[206:209], v[28:31]
	v_mfma_f32_16x16x32_bf16 v[20:23], v[158:161], v[206:209], v[20:23]
	v_mfma_f32_16x16x32_bf16 v[12:15], v[150:153], v[214:217], v[12:15]
	v_mfma_f32_16x16x32_bf16 v[4:7], v[158:161], v[214:217], v[4:7]
	v_mfma_f32_16x16x32_bf16 v[60:63], v[154:157], v[186:189], v[60:63]
	v_mfma_f32_16x16x32_bf16 v[52:55], v[162:165], v[186:189], v[52:55]
	v_mfma_f32_16x16x32_bf16 v[44:47], v[154:157], v[202:205], v[44:47]
	v_mfma_f32_16x16x32_bf16 v[36:39], v[162:165], v[202:205], v[36:39]
	v_mfma_f32_16x16x32_bf16 v[28:31], v[154:157], v[210:213], v[28:31]
	v_mfma_f32_16x16x32_bf16 v[20:23], v[162:165], v[210:213], v[20:23]
	v_mfma_f32_16x16x32_bf16 v[12:15], v[154:157], v[218:221], v[12:15]
	v_mfma_f32_16x16x32_bf16 v[4:7], v[162:165], v[218:221], v[4:7]
	s_setprio 0
	s_setprio 1
	v_mfma_f32_16x16x32_bf16 v[56:59], v[166:169], v[182:185], v[56:59]
	v_mfma_f32_16x16x32_bf16 v[48:51], v[174:177], v[182:185], v[48:51]
	v_mfma_f32_16x16x32_bf16 v[40:43], v[166:169], v[190:193], v[40:43]
	v_mfma_f32_16x16x32_bf16 v[32:35], v[174:177], v[190:193], v[32:35]
	v_mfma_f32_16x16x32_bf16 v[24:27], v[166:169], v[206:209], v[24:27]
	v_mfma_f32_16x16x32_bf16 v[16:19], v[174:177], v[206:209], v[16:19]
	v_mfma_f32_16x16x32_bf16 v[8:11], v[166:169], v[214:217], v[8:11]
	v_mfma_f32_16x16x32_bf16 v[0:3], v[174:177], v[214:217], v[0:3]
	v_mfma_f32_16x16x32_bf16 v[56:59], v[170:173], v[186:189], v[56:59]
	v_mfma_f32_16x16x32_bf16 v[48:51], v[178:181], v[186:189], v[48:51]
	v_mfma_f32_16x16x32_bf16 v[40:43], v[170:173], v[202:205], v[40:43]
	v_mfma_f32_16x16x32_bf16 v[32:35], v[178:181], v[202:205], v[32:35]
	v_mfma_f32_16x16x32_bf16 v[24:27], v[170:173], v[210:213], v[24:27]
	v_mfma_f32_16x16x32_bf16 v[16:19], v[178:181], v[210:213], v[16:19]
	v_mfma_f32_16x16x32_bf16 v[8:11], v[170:173], v[218:221], v[8:11]
	v_mfma_f32_16x16x32_bf16 v[0:3], v[178:181], v[218:221], v[0:3]
	s_setprio 0
	s_add_i32 s54, s54, 2
	s_add_u32 s24, s24, 0x100
	s_addc_u32 s25, s25, 0
	s_add_u32 s52, s52, 0x100
	s_addc_u32 s53, s53, 0
	s_cmp_gt_u32 s54, 13
	s_barrier
	s_cbranch_scc1 .Lgu_kdone
.LBB0_146:
	s_add_u32 s26, s24, 0xfffc0080
	s_addc_u32 s27, s25, -1
	s_add_i32 s55, 0, 0x10000
	s_cmp_eq_u32 s54, 12
	s_cselect_b32 s29, s17, s27
	s_cselect_b32 s28, s50, s26
	v_add_u32_e32 v140, s55, v143
	s_cselect_b32 s27, s15, s53
	s_cselect_b32 s26, s51, s52
	s_add_i32 s60, 0, 0x14000
	ds_read_b128 v[150:153], v140
	ds_read_b128 v[154:157], v140 offset:1024
	ds_read_b128 v[158:161], v140 offset:2048
	ds_read_b128 v[162:165], v140 offset:3072
	v_add_u32_e32 v140, s60, v143
	ds_read_b128 v[166:169], v140
	ds_read_b128 v[170:173], v140 offset:1024
	ds_read_b128 v[174:177], v140 offset:2048
	ds_read_b128 v[178:181], v140 offset:3072
	v_lshl_add_u64 v[140:141], s[24:25], 0, v[136:137]
	s_add_i32 m0, s40, 0xc000
	ds_read_b128 v[182:185], v148
	ds_read_b128 v[186:189], v148 offset:1024
	ds_read_b128 v[190:193], v148 offset:2048
	ds_read_b128 v[202:205], v148 offset:3072
	ds_read_b128 v[206:209], v148 offset:4096
	ds_read_b128 v[210:213], v148 offset:5120
	ds_read_b128 v[214:217], v148 offset:6144
	ds_read_b128 v[218:221], v148 offset:7168
	global_load_lds_dwordx4 v[140:141], off
	v_lshl_add_u64 v[140:141], s[24:25], 0, v[138:139]
	s_add_i32 m0, s40, 0xe000
	s_nop 0
	global_load_lds_dwordx4 v[140:141], off
	s_waitcnt vmcnt(8)
	s_waitcnt lgkmcnt(0)
	s_barrier
	s_setprio 1
	s_waitcnt lgkmcnt(0)
	v_mfma_f32_16x16x32_bf16 v[126:129], v[150:153], v[182:185], v[126:129]
	v_mfma_f32_16x16x32_bf16 v[118:121], v[158:161], v[182:185], v[118:121]
	v_mfma_f32_16x16x32_bf16 v[110:113], v[150:153], v[190:193], v[110:113]
	v_mfma_f32_16x16x32_bf16 v[102:105], v[158:161], v[190:193], v[102:105]
	v_mfma_f32_16x16x32_bf16 v[92:95], v[150:153], v[206:209], v[92:95]
	v_mfma_f32_16x16x32_bf16 v[84:87], v[158:161], v[206:209], v[84:87]
	v_mfma_f32_16x16x32_bf16 v[76:79], v[150:153], v[214:217], v[76:79]
	v_mfma_f32_16x16x32_bf16 v[68:71], v[158:161], v[214:217], v[68:71]
	v_mfma_f32_16x16x32_bf16 v[126:129], v[154:157], v[186:189], v[126:129]
	v_mfma_f32_16x16x32_bf16 v[118:121], v[162:165], v[186:189], v[118:121]
	v_mfma_f32_16x16x32_bf16 v[110:113], v[154:157], v[202:205], v[110:113]
	v_mfma_f32_16x16x32_bf16 v[102:105], v[162:165], v[202:205], v[102:105]
	v_mfma_f32_16x16x32_bf16 v[92:95], v[154:157], v[210:213], v[92:95]
	v_mfma_f32_16x16x32_bf16 v[84:87], v[162:165], v[210:213], v[84:87]
	v_mfma_f32_16x16x32_bf16 v[76:79], v[154:157], v[218:221], v[76:79]
	v_mfma_f32_16x16x32_bf16 v[68:71], v[162:165], v[218:221], v[68:71]
	s_setprio 0
	s_setprio 1
	v_mfma_f32_16x16x32_bf16 v[122:125], v[166:169], v[182:185], v[122:125]
	v_mfma_f32_16x16x32_bf16 v[114:117], v[174:177], v[182:185], v[114:117]
	v_mfma_f32_16x16x32_bf16 v[106:109], v[166:169], v[190:193], v[106:109]
	v_mfma_f32_16x16x32_bf16 v[98:101], v[174:177], v[190:193], v[98:101]
	v_mfma_f32_16x16x32_bf16 v[88:91], v[166:169], v[206:209], v[88:91]
	v_mfma_f32_16x16x32_bf16 v[80:83], v[174:177], v[206:209], v[80:83]
	v_mfma_f32_16x16x32_bf16 v[72:75], v[166:169], v[214:217], v[72:75]
	v_mfma_f32_16x16x32_bf16 v[64:67], v[174:177], v[214:217], v[64:67]
	v_mfma_f32_16x16x32_bf16 v[122:125], v[170:173], v[186:189], v[122:125]
	v_mfma_f32_16x16x32_bf16 v[114:117], v[178:181], v[186:189], v[114:117]
	v_mfma_f32_16x16x32_bf16 v[106:109], v[170:173], v[202:205], v[106:109]
	v_mfma_f32_16x16x32_bf16 v[98:101], v[178:181], v[202:205], v[98:101]
	v_mfma_f32_16x16x32_bf16 v[88:91], v[170:173], v[210:213], v[88:91]
	v_mfma_f32_16x16x32_bf16 v[80:83], v[178:181], v[210:213], v[80:83]
	v_mfma_f32_16x16x32_bf16 v[72:75], v[170:173], v[218:221], v[72:75]
	v_mfma_f32_16x16x32_bf16 v[64:67], v[178:181], v[218:221], v[64:67]
	s_setprio 0
	s_barrier
	s_add_i32 s55, s55, s39
	v_lshl_add_u64 v[140:141], s[26:27], 0, v[96:97]
	s_mov_b32 m0, s55
	ds_read_b128 v[182:185], v148 offset:16384
	ds_read_b128 v[186:189], v148 offset:17408
	ds_read_b128 v[190:193], v148 offset:18432
	ds_read_b128 v[202:205], v148 offset:19456
	ds_read_b128 v[206:209], v148 offset:20480
	ds_read_b128 v[210:213], v148 offset:21504
	ds_read_b128 v[214:217], v148 offset:22528
	ds_read_b128 v[218:221], v148 offset:23552
	global_load_lds_dwordx4 v[140:141], off
	s_add_i32 m0, s55, 0x2000
	s_add_u32 s56, s26, 0x40000
	v_lshl_add_u64 v[194:195], s[26:27], 0, v[130:131]
	s_addc_u32 s57, s27, 0
	s_add_i32 s55, s60, s39
	global_load_lds_dwordx4 v[194:195], off
	v_lshl_add_u64 v[196:197], s[56:57], 0, v[96:97]
	s_mov_b32 m0, s55
	v_lshl_add_u64 v[198:199], s[28:29], 0, v[132:133]
	global_load_lds_dwordx4 v[196:197], off
	v_lshl_add_u64 v[196:197], s[56:57], 0, v[130:131]
	s_add_i32 m0, s55, 0x2000
	s_nop 0
	global_load_lds_dwordx4 v[196:197], off
	v_lshl_add_u64 v[196:197], s[28:29], 0, v[134:135]
	s_mov_b32 m0, s40
	s_nop 0
	global_load_lds_dwordx4 v[196:197], off
	s_mov_b32 m0, s41
	s_nop 0
	global_load_lds_dwordx4 v[198:199], off
	s_waitcnt vmcnt(8)
	s_waitcnt lgkmcnt(0)
	s_barrier
	s_setprio 1
	s_waitcnt lgkmcnt(0)
	v_mfma_f32_16x16x32_bf16 v[60:63], v[150:153], v[182:185], v[60:63]
	v_mfma_f32_16x16x32_bf16 v[52:55], v[158:161], v[182:185], v[52:55]
	v_mfma_f32_16x16x32_bf16 v[44:47], v[150:153], v[190:193], v[44:47]
	v_mfma_f32_16x16x32_bf16 v[36:39], v[158:161], v[190:193], v[36:39]
	v_mfma_f32_16x16x32_bf16 v[28:31], v[150:153], v[206:209], v[28:31]
	v_mfma_f32_16x16x32_bf16 v[20:23], v[158:161], v[206:209], v[20:23]
	v_mfma_f32_16x16x32_bf16 v[12:15], v[150:153], v[214:217], v[12:15]
	v_mfma_f32_16x16x32_bf16 v[4:7], v[158:161], v[214:217], v[4:7]
	v_mfma_f32_16x16x32_bf16 v[60:63], v[154:157], v[186:189], v[60:63]
	v_mfma_f32_16x16x32_bf16 v[52:55], v[162:165], v[186:189], v[52:55]
	v_mfma_f32_16x16x32_bf16 v[44:47], v[154:157], v[202:205], v[44:47]
	v_mfma_f32_16x16x32_bf16 v[36:39], v[162:165], v[202:205], v[36:39]
	v_mfma_f32_16x16x32_bf16 v[28:31], v[154:157], v[210:213], v[28:31]
	v_mfma_f32_16x16x32_bf16 v[20:23], v[162:165], v[210:213], v[20:23]
	v_mfma_f32_16x16x32_bf16 v[12:15], v[154:157], v[218:221], v[12:15]
	v_mfma_f32_16x16x32_bf16 v[4:7], v[162:165], v[218:221], v[4:7]
	s_setprio 0
	s_setprio 1
	v_mfma_f32_16x16x32_bf16 v[56:59], v[166:169], v[182:185], v[56:59]
	v_mfma_f32_16x16x32_bf16 v[48:51], v[174:177], v[182:185], v[48:51]
	v_mfma_f32_16x16x32_bf16 v[40:43], v[166:169], v[190:193], v[40:43]
	v_mfma_f32_16x16x32_bf16 v[32:35], v[174:177], v[190:193], v[32:35]
	v_mfma_f32_16x16x32_bf16 v[24:27], v[166:169], v[206:209], v[24:27]
	v_mfma_f32_16x16x32_bf16 v[16:19], v[174:177], v[206:209], v[16:19]
	v_mfma_f32_16x16x32_bf16 v[8:11], v[166:169], v[214:217], v[8:11]
	v_mfma_f32_16x16x32_bf16 v[0:3], v[174:177], v[214:217], v[0:3]
	v_mfma_f32_16x16x32_bf16 v[56:59], v[170:173], v[186:189], v[56:59]
	v_mfma_f32_16x16x32_bf16 v[48:51], v[178:181], v[186:189], v[48:51]
	v_mfma_f32_16x16x32_bf16 v[40:43], v[170:173], v[202:205], v[40:43]
	v_mfma_f32_16x16x32_bf16 v[32:35], v[178:181], v[202:205], v[32:35]
	v_mfma_f32_16x16x32_bf16 v[24:27], v[170:173], v[210:213], v[24:27]
	v_mfma_f32_16x16x32_bf16 v[16:19], v[178:181], v[210:213], v[16:19]
	v_mfma_f32_16x16x32_bf16 v[8:11], v[170:173], v[218:221], v[8:11]
	v_mfma_f32_16x16x32_bf16 v[0:3], v[178:181], v[218:221], v[0:3]
	s_setprio 0
	s_barrier
	s_add_i32 s55, 0, 0x18000
	v_add_u32_e32 v149, s55, v143
	s_add_i32 s56, 0, 0x1c000
	ds_read_b128 v[150:153], v149
	ds_read_b128 v[154:157], v149 offset:1024
	ds_read_b128 v[158:161], v149 offset:2048
	ds_read_b128 v[162:165], v149 offset:3072
	v_add_u32_e32 v149, s56, v143
	ds_read_b128 v[166:169], v149
	ds_read_b128 v[170:173], v149 offset:1024
	ds_read_b128 v[174:177], v149 offset:2048
	ds_read_b128 v[178:181], v149 offset:3072
	s_add_u32 s28, s28, 0x40000
	s_addc_u32 s29, s29, 0
	s_mov_b32 m0, s42
	v_lshl_add_u64 v[200:201], s[28:29], 0, v[134:135]
	ds_read_b128 v[182:185], v148 offset:32768
	ds_read_b128 v[186:189], v148 offset:33792
	ds_read_b128 v[190:193], v148 offset:34816
	ds_read_b128 v[202:205], v148 offset:35840
	ds_read_b128 v[206:209], v148 offset:36864
	ds_read_b128 v[210:213], v148 offset:37888
	ds_read_b128 v[214:217], v148 offset:38912
	ds_read_b128 v[218:221], v148 offset:39936
	global_load_lds_dwordx4 v[200:201], off
	v_lshl_add_u64 v[200:201], s[28:29], 0, v[132:133]
	s_mov_b32 m0, s43
	s_nop 0
	global_load_lds_dwordx4 v[200:201], off
	s_waitcnt vmcnt(8)
	s_waitcnt lgkmcnt(0)
	s_barrier
	s_setprio 1
	s_waitcnt lgkmcnt(0)
	v_mfma_f32_16x16x32_bf16 v[126:129], v[150:153], v[182:185], v[126:129]
	v_mfma_f32_16x16x32_bf16 v[118:121], v[158:161], v[182:185], v[118:121]
	v_mfma_f32_16x16x32_bf16 v[110:113], v[150:153], v[190:193], v[110:113]
	v_mfma_f32_16x16x32_bf16 v[102:105], v[158:161], v[190:193], v[102:105]
	v_mfma_f32_16x16x32_bf16 v[92:95], v[150:153], v[206:209], v[92:95]
	v_mfma_f32_16x16x32_bf16 v[84:87], v[158:161], v[206:209], v[84:87]
	v_mfma_f32_16x16x32_bf16 v[76:79], v[150:153], v[214:217], v[76:79]
	v_mfma_f32_16x16x32_bf16 v[68:71], v[158:161], v[214:217], v[68:71]
	v_mfma_f32_16x16x32_bf16 v[126:129], v[154:157], v[186:189], v[126:129]
	v_mfma_f32_16x16x32_bf16 v[118:121], v[162:165], v[186:189], v[118:121]
	v_mfma_f32_16x16x32_bf16 v[110:113], v[154:157], v[202:205], v[110:113]
	v_mfma_f32_16x16x32_bf16 v[102:105], v[162:165], v[202:205], v[102:105]
	v_mfma_f32_16x16x32_bf16 v[92:95], v[154:157], v[210:213], v[92:95]
	v_mfma_f32_16x16x32_bf16 v[84:87], v[162:165], v[210:213], v[84:87]
	v_mfma_f32_16x16x32_bf16 v[76:79], v[154:157], v[218:221], v[76:79]
	v_mfma_f32_16x16x32_bf16 v[68:71], v[162:165], v[218:221], v[68:71]
	s_setprio 0
	s_setprio 1
	v_mfma_f32_16x16x32_bf16 v[122:125], v[166:169], v[182:185], v[122:125]
	v_mfma_f32_16x16x32_bf16 v[114:117], v[174:177], v[182:185], v[114:117]
	v_mfma_f32_16x16x32_bf16 v[106:109], v[166:169], v[190:193], v[106:109]
	v_mfma_f32_16x16x32_bf16 v[98:101], v[174:177], v[190:193], v[98:101]
	v_mfma_f32_16x16x32_bf16 v[88:91], v[166:169], v[206:209], v[88:91]
	v_mfma_f32_16x16x32_bf16 v[80:83], v[174:177], v[206:209], v[80:83]
	v_mfma_f32_16x16x32_bf16 v[72:75], v[166:169], v[214:217], v[72:75]
	v_mfma_f32_16x16x32_bf16 v[64:67], v[174:177], v[214:217], v[64:67]
	v_mfma_f32_16x16x32_bf16 v[122:125], v[170:173], v[186:189], v[122:125]
	v_mfma_f32_16x16x32_bf16 v[114:117], v[178:181], v[186:189], v[114:117]
	v_mfma_f32_16x16x32_bf16 v[106:109], v[170:173], v[202:205], v[106:109]
	v_mfma_f32_16x16x32_bf16 v[98:101], v[178:181], v[202:205], v[98:101]
	v_mfma_f32_16x16x32_bf16 v[88:91], v[170:173], v[210:213], v[88:91]
	v_mfma_f32_16x16x32_bf16 v[80:83], v[178:181], v[210:213], v[80:83]
	v_mfma_f32_16x16x32_bf16 v[72:75], v[170:173], v[218:221], v[72:75]
	v_mfma_f32_16x16x32_bf16 v[64:67], v[178:181], v[218:221], v[64:67]
	s_setprio 0
	s_barrier
	s_add_i32 s28, s55, s39
	v_lshl_add_u64 v[140:141], v[140:141], 0, s[64:65]
	s_mov_b32 m0, s28
	ds_read_b128 v[182:185], v148 offset:49152
	ds_read_b128 v[186:189], v148 offset:50176
	ds_read_b128 v[190:193], v148 offset:51200
	ds_read_b128 v[202:205], v148 offset:52224
	ds_read_b128 v[206:209], v148 offset:53248
	ds_read_b128 v[210:213], v148 offset:54272
	ds_read_b128 v[214:217], v148 offset:55296
	ds_read_b128 v[218:221], v148 offset:56320
	global_load_lds_dwordx4 v[140:141], off
	s_add_i32 m0, s28, 0x2000
	s_add_u32 s26, s26, 0x40080
	v_lshl_add_u64 v[140:141], v[194:195], 0, s[64:65]
	s_addc_u32 s27, s27, 0
	s_add_i32 s28, s56, s39
	global_load_lds_dwordx4 v[140:141], off
	v_lshl_add_u64 v[140:141], s[26:27], 0, v[96:97]
	s_mov_b32 m0, s28
	s_nop 0
	global_load_lds_dwordx4 v[140:141], off
	v_lshl_add_u64 v[140:141], s[26:27], 0, v[130:131]
	s_add_i32 m0, s28, 0x2000
	s_nop 0
	global_load_lds_dwordx4 v[140:141], off
	v_lshl_add_u64 v[140:141], v[196:197], 0, s[64:65]
	s_mov_b32 m0, s44
	s_nop 0
	global_load_lds_dwordx4 v[140:141], off
	v_lshl_add_u64 v[140:141], v[198:199], 0, s[64:65]
	s_mov_b32 m0, s45
	s_nop 0
	global_load_lds_dwordx4 v[140:141], off
	s_waitcnt vmcnt(8)
	s_waitcnt lgkmcnt(0)
	s_barrier
	s_setprio 1
	s_waitcnt lgkmcnt(0)
	v_mfma_f32_16x16x32_bf16 v[60:63], v[150:153], v[182:185], v[60:63]
	v_mfma_f32_16x16x32_bf16 v[52:55], v[158:161], v[182:185], v[52:55]
	v_mfma_f32_16x16x32_bf16 v[44:47], v[150:153], v[190:193], v[44:47]
	v_mfma_f32_16x16x32_bf16 v[36:39], v[158:161], v[190:193], v[36:39]
	v_mfma_f32_16x16x32_bf16 v[28:31], v[150:153], v[206:209], v[28:31]
	v_mfma_f32_16x16x32_bf16 v[20:23], v[158:161], v[206:209], v[20:23]
	v_mfma_f32_16x16x32_bf16 v[12:15], v[150:153], v[214:217], v[12:15]
	v_mfma_f32_16x16x32_bf16 v[4:7], v[158:161], v[214:217], v[4:7]
	v_mfma_f32_16x16x32_bf16 v[60:63], v[154:157], v[186:189], v[60:63]
	v_mfma_f32_16x16x32_bf16 v[52:55], v[162:165], v[186:189], v[52:55]
	v_mfma_f32_16x16x32_bf16 v[44:47], v[154:157], v[202:205], v[44:47]
	v_mfma_f32_16x16x32_bf16 v[36:39], v[162:165], v[202:205], v[36:39]
	v_mfma_f32_16x16x32_bf16 v[28:31], v[154:157], v[210:213], v[28:31]
	v_mfma_f32_16x16x32_bf16 v[20:23], v[162:165], v[210:213], v[20:23]
	v_mfma_f32_16x16x32_bf16 v[12:15], v[154:157], v[218:221], v[12:15]
	v_mfma_f32_16x16x32_bf16 v[4:7], v[162:165], v[218:221], v[4:7]
	s_setprio 0
	s_setprio 1
	v_mfma_f32_16x16x32_bf16 v[56:59], v[166:169], v[182:185], v[56:59]
	v_mfma_f32_16x16x32_bf16 v[48:51], v[174:177], v[182:185], v[48:51]
	v_mfma_f32_16x16x32_bf16 v[40:43], v[166:169], v[190:193], v[40:43]
	v_mfma_f32_16x16x32_bf16 v[32:35], v[174:177], v[190:193], v[32:35]
	v_mfma_f32_16x16x32_bf16 v[24:27], v[166:169], v[206:209], v[24:27]
	v_mfma_f32_16x16x32_bf16 v[16:19], v[174:177], v[206:209], v[16:19]
	v_mfma_f32_16x16x32_bf16 v[8:11], v[166:169], v[214:217], v[8:11]
	v_mfma_f32_16x16x32_bf16 v[0:3], v[174:177], v[214:217], v[0:3]
	v_mfma_f32_16x16x32_bf16 v[56:59], v[170:173], v[186:189], v[56:59]
	v_mfma_f32_16x16x32_bf16 v[48:51], v[178:181], v[186:189], v[48:51]
	v_mfma_f32_16x16x32_bf16 v[40:43], v[170:173], v[202:205], v[40:43]
	v_mfma_f32_16x16x32_bf16 v[32:35], v[178:181], v[202:205], v[32:35]
	v_mfma_f32_16x16x32_bf16 v[24:27], v[170:173], v[210:213], v[24:27]
	v_mfma_f32_16x16x32_bf16 v[16:19], v[178:181], v[210:213], v[16:19]
	v_mfma_f32_16x16x32_bf16 v[8:11], v[170:173], v[218:221], v[8:11]
	v_mfma_f32_16x16x32_bf16 v[0:3], v[178:181], v[218:221], v[0:3]
	s_setprio 0
	s_add_i32 s54, s54, 2
	s_add_u32 s24, s24, 0x100
	s_addc_u32 s25, s25, 0
	s_add_u32 s52, s52, 0x100
	s_addc_u32 s53, s53, 0
	s_cmp_gt_u32 s54, 13
	s_barrier
	s_cbranch_scc0 .LBB0_146

.LBB0_339:
	s_add_u32 s6, s26, 0x100
	s_addc_u32 s7, s27, 0
	s_add_i32 s56, 0, 0x10000
	s_cmp_eq_u32 s55, 40
	s_cselect_b32 s31, s23, s7
	s_cselect_b32 s30, s22, s6
	s_cselect_b32 s29, s25, s54
	s_cselect_b32 s28, s24, s53
	s_add_i32 s57, 0, 0x14000
	v_add_u32_e32 v106, s56, v254
	v_add_u32_e32 v150, s57, v254
	ds_read_b128 v[72:75], v106
	ds_read_b128 v[84:87], v106 offset:1024
	ds_read_b128 v[98:101], v106 offset:2048
	ds_read_b128 v[106:109], v106 offset:3072
	ds_read_b128 v[122:125], v150
	ds_read_b128 v[126:129], v150 offset:1024
	ds_read_b128 v[142:145], v150 offset:2048
	ds_read_b128 v[150:153], v150 offset:3072
	v_lshl_add_u64 v[194:195], s[26:27], 0, v[208:209]
	s_add_i32 m0, s40, 0xc000
	ds_read_b128 v[162:165], v198
	ds_read_b128 v[166:169], v198 offset:1024
	ds_read_b128 v[170:173], v198 offset:2048
	ds_read_b128 v[174:177], v198 offset:3072
	ds_read_b128 v[178:181], v198 offset:4096
	ds_read_b128 v[182:185], v198 offset:5120
	ds_read_b128 v[186:189], v198 offset:6144
	ds_read_b128 v[190:193], v198 offset:7168
	global_load_lds_dwordx4 v[194:195], off
	v_lshl_add_u64 v[194:195], s[26:27], 0, v[210:211]
	s_add_i32 m0, s40, 0xe000
	s_nop 0
	global_load_lds_dwordx4 v[194:195], off
	s_waitcnt vmcnt(8)
	s_waitcnt lgkmcnt(0)
	s_barrier
	s_setprio 1
	s_waitcnt lgkmcnt(0)
	v_mfma_f32_16x16x32_bf16 v[158:161], v[72:75], v[162:165], v[158:161]
	v_mfma_f32_16x16x32_bf16 v[154:157], v[98:101], v[162:165], v[154:157]
	v_mfma_f32_16x16x32_bf16 v[134:137], v[72:75], v[170:173], v[134:137]
	v_mfma_f32_16x16x32_bf16 v[130:133], v[98:101], v[170:173], v[130:133]
	v_mfma_f32_16x16x32_bf16 v[110:113], v[72:75], v[178:181], v[110:113]
	v_mfma_f32_16x16x32_bf16 v[102:105], v[98:101], v[178:181], v[102:105]
	v_mfma_f32_16x16x32_bf16 v[80:83], v[72:75], v[186:189], v[80:83]
	v_mfma_f32_16x16x32_bf16 v[76:79], v[98:101], v[186:189], v[76:79]
	v_mfma_f32_16x16x32_bf16 v[158:161], v[84:87], v[166:169], v[158:161]
	v_mfma_f32_16x16x32_bf16 v[154:157], v[106:109], v[166:169], v[154:157]
	v_mfma_f32_16x16x32_bf16 v[134:137], v[84:87], v[174:177], v[134:137]
	v_mfma_f32_16x16x32_bf16 v[130:133], v[106:109], v[174:177], v[130:133]
	v_mfma_f32_16x16x32_bf16 v[110:113], v[84:87], v[182:185], v[110:113]
	v_mfma_f32_16x16x32_bf16 v[102:105], v[106:109], v[182:185], v[102:105]
	v_mfma_f32_16x16x32_bf16 v[80:83], v[84:87], v[190:193], v[80:83]
	v_mfma_f32_16x16x32_bf16 v[76:79], v[106:109], v[190:193], v[76:79]
	s_setprio 0
	s_setprio 1
	v_mfma_f32_16x16x32_bf16 v[146:149], v[122:125], v[162:165], v[146:149]
	v_mfma_f32_16x16x32_bf16 v[138:141], v[142:145], v[162:165], v[138:141]
	v_mfma_f32_16x16x32_bf16 v[118:121], v[122:125], v[170:173], v[118:121]
	v_mfma_f32_16x16x32_bf16 v[114:117], v[142:145], v[170:173], v[114:117]
	v_mfma_f32_16x16x32_bf16 v[92:95], v[122:125], v[178:181], v[92:95]
	v_mfma_f32_16x16x32_bf16 v[88:91], v[142:145], v[178:181], v[88:91]
	v_mfma_f32_16x16x32_bf16 v[68:71], v[122:125], v[186:189], v[68:71]
	v_mfma_f32_16x16x32_bf16 v[64:67], v[142:145], v[186:189], v[64:67]
	v_mfma_f32_16x16x32_bf16 v[146:149], v[126:129], v[166:169], v[146:149]
	v_mfma_f32_16x16x32_bf16 v[138:141], v[150:153], v[166:169], v[138:141]
	v_mfma_f32_16x16x32_bf16 v[118:121], v[126:129], v[174:177], v[118:121]
	v_mfma_f32_16x16x32_bf16 v[114:117], v[150:153], v[174:177], v[114:117]
	v_mfma_f32_16x16x32_bf16 v[92:95], v[126:129], v[182:185], v[92:95]
	v_mfma_f32_16x16x32_bf16 v[88:91], v[150:153], v[182:185], v[88:91]
	v_mfma_f32_16x16x32_bf16 v[68:71], v[126:129], v[190:193], v[68:71]
	v_mfma_f32_16x16x32_bf16 v[64:67], v[150:153], v[190:193], v[64:67]
	s_setprio 0
	s_barrier
	s_add_i32 s26, s56, s39
	v_lshl_add_u64 v[194:195], s[28:29], 0, v[96:97]
	s_mov_b32 m0, s26
	ds_read_b128 v[162:165], v198 offset:16384
	ds_read_b128 v[166:169], v198 offset:17408
	ds_read_b128 v[170:173], v198 offset:18432
	ds_read_b128 v[174:177], v198 offset:19456
	ds_read_b128 v[178:181], v198 offset:20480
	ds_read_b128 v[182:185], v198 offset:21504
	ds_read_b128 v[186:189], v198 offset:22528
	ds_read_b128 v[190:193], v198 offset:23552
	global_load_lds_dwordx4 v[194:195], off
	s_add_i32 m0, s26, 0x2000
	s_add_u32 s26, s28, 0xb0000
	v_lshl_add_u64 v[196:197], s[28:29], 0, v[206:207]
	s_addc_u32 s27, s29, 0
	s_add_i32 s56, s57, s39
	global_load_lds_dwordx4 v[196:197], off
	v_lshl_add_u64 v[200:201], s[26:27], 0, v[96:97]
	s_mov_b32 m0, s56
	v_lshl_add_u64 v[212:213], s[30:31], 0, v[204:205]
	global_load_lds_dwordx4 v[200:201], off
	v_lshl_add_u64 v[200:201], s[26:27], 0, v[206:207]
	s_add_i32 m0, s56, 0x2000
	s_nop 0
	global_load_lds_dwordx4 v[200:201], off
	v_lshl_add_u64 v[200:201], s[30:31], 0, v[202:203]
	s_mov_b32 m0, s40
	s_nop 0
	global_load_lds_dwordx4 v[200:201], off
	s_mov_b32 m0, s41
	s_nop 0
	global_load_lds_dwordx4 v[212:213], off
	s_waitcnt vmcnt(8)
	s_waitcnt lgkmcnt(0)
	s_barrier
	s_setprio 1
	s_waitcnt lgkmcnt(0)
	v_mfma_f32_16x16x32_bf16 v[60:63], v[72:75], v[162:165], v[60:63]
	v_mfma_f32_16x16x32_bf16 v[56:59], v[98:101], v[162:165], v[56:59]
	v_mfma_f32_16x16x32_bf16 v[44:47], v[72:75], v[170:173], v[44:47]
	v_mfma_f32_16x16x32_bf16 v[40:43], v[98:101], v[170:173], v[40:43]
	v_mfma_f32_16x16x32_bf16 v[28:31], v[72:75], v[178:181], v[28:31]
	v_mfma_f32_16x16x32_bf16 v[24:27], v[98:101], v[178:181], v[24:27]
	v_mfma_f32_16x16x32_bf16 v[12:15], v[72:75], v[186:189], v[12:15]
	v_mfma_f32_16x16x32_bf16 v[8:11], v[98:101], v[186:189], v[8:11]
	v_mfma_f32_16x16x32_bf16 v[60:63], v[84:87], v[166:169], v[60:63]
	v_mfma_f32_16x16x32_bf16 v[56:59], v[106:109], v[166:169], v[56:59]
	v_mfma_f32_16x16x32_bf16 v[44:47], v[84:87], v[174:177], v[44:47]
	v_mfma_f32_16x16x32_bf16 v[40:43], v[106:109], v[174:177], v[40:43]
	v_mfma_f32_16x16x32_bf16 v[28:31], v[84:87], v[182:185], v[28:31]
	v_mfma_f32_16x16x32_bf16 v[24:27], v[106:109], v[182:185], v[24:27]
	v_mfma_f32_16x16x32_bf16 v[12:15], v[84:87], v[190:193], v[12:15]
	v_mfma_f32_16x16x32_bf16 v[8:11], v[106:109], v[190:193], v[8:11]
	s_setprio 0
	s_setprio 1
	v_mfma_f32_16x16x32_bf16 v[52:55], v[122:125], v[162:165], v[52:55]
	v_mfma_f32_16x16x32_bf16 v[48:51], v[142:145], v[162:165], v[48:51]
	v_mfma_f32_16x16x32_bf16 v[36:39], v[122:125], v[170:173], v[36:39]
	v_mfma_f32_16x16x32_bf16 v[32:35], v[142:145], v[170:173], v[32:35]
	v_mfma_f32_16x16x32_bf16 v[20:23], v[122:125], v[178:181], v[20:23]
	v_mfma_f32_16x16x32_bf16 v[16:19], v[142:145], v[178:181], v[16:19]
	v_mfma_f32_16x16x32_bf16 v[4:7], v[122:125], v[186:189], v[4:7]
	v_mfma_f32_16x16x32_bf16 v[0:3], v[142:145], v[186:189], v[0:3]
	v_mfma_f32_16x16x32_bf16 v[52:55], v[126:129], v[166:169], v[52:55]
	v_mfma_f32_16x16x32_bf16 v[48:51], v[150:153], v[166:169], v[48:51]
	v_mfma_f32_16x16x32_bf16 v[36:39], v[126:129], v[174:177], v[36:39]
	v_mfma_f32_16x16x32_bf16 v[32:35], v[150:153], v[174:177], v[32:35]
	v_mfma_f32_16x16x32_bf16 v[20:23], v[126:129], v[182:185], v[20:23]
	v_mfma_f32_16x16x32_bf16 v[16:19], v[150:153], v[182:185], v[16:19]
	v_mfma_f32_16x16x32_bf16 v[4:7], v[126:129], v[190:193], v[4:7]
	v_mfma_f32_16x16x32_bf16 v[0:3], v[150:153], v[190:193], v[0:3]
	s_setprio 0
	s_barrier
	s_add_i32 s56, 0, 0x18000
	s_add_i32 s57, 0, 0x1c000
	v_add_u32_e32 v106, s56, v254
	v_add_u32_e32 v150, s57, v254
	ds_read_b128 v[72:75], v106
	ds_read_b128 v[84:87], v106 offset:1024
	ds_read_b128 v[98:101], v106 offset:2048
	ds_read_b128 v[106:109], v106 offset:3072
	ds_read_b128 v[122:125], v150
	ds_read_b128 v[126:129], v150 offset:1024
	ds_read_b128 v[142:145], v150 offset:2048
	ds_read_b128 v[150:153], v150 offset:3072
	s_add_u32 s26, s30, 0xb0000
	s_addc_u32 s27, s31, 0
	s_mov_b32 m0, s42
	v_lshl_add_u64 v[214:215], s[26:27], 0, v[202:203]
	ds_read_b128 v[162:165], v198 offset:32768
	ds_read_b128 v[166:169], v198 offset:33792
	ds_read_b128 v[170:173], v198 offset:34816
	ds_read_b128 v[174:177], v198 offset:35840
	ds_read_b128 v[178:181], v198 offset:36864
	ds_read_b128 v[182:185], v198 offset:37888
	ds_read_b128 v[186:189], v198 offset:38912
	ds_read_b128 v[190:193], v198 offset:39936
	global_load_lds_dwordx4 v[214:215], off
	v_lshl_add_u64 v[214:215], s[26:27], 0, v[204:205]
	s_mov_b32 m0, s43
	s_nop 0
	global_load_lds_dwordx4 v[214:215], off
	s_waitcnt vmcnt(8)
	s_waitcnt lgkmcnt(0)
	s_barrier
	s_setprio 1
	s_waitcnt lgkmcnt(0)
	v_mfma_f32_16x16x32_bf16 v[158:161], v[72:75], v[162:165], v[158:161]
	v_mfma_f32_16x16x32_bf16 v[154:157], v[98:101], v[162:165], v[154:157]
	v_mfma_f32_16x16x32_bf16 v[134:137], v[72:75], v[170:173], v[134:137]
	v_mfma_f32_16x16x32_bf16 v[130:133], v[98:101], v[170:173], v[130:133]
	v_mfma_f32_16x16x32_bf16 v[110:113], v[72:75], v[178:181], v[110:113]
	v_mfma_f32_16x16x32_bf16 v[102:105], v[98:101], v[178:181], v[102:105]
	v_mfma_f32_16x16x32_bf16 v[80:83], v[72:75], v[186:189], v[80:83]
	v_mfma_f32_16x16x32_bf16 v[76:79], v[98:101], v[186:189], v[76:79]
	v_mfma_f32_16x16x32_bf16 v[158:161], v[84:87], v[166:169], v[158:161]
	v_mfma_f32_16x16x32_bf16 v[154:157], v[106:109], v[166:169], v[154:157]
	v_mfma_f32_16x16x32_bf16 v[134:137], v[84:87], v[174:177], v[134:137]
	v_mfma_f32_16x16x32_bf16 v[130:133], v[106:109], v[174:177], v[130:133]
	v_mfma_f32_16x16x32_bf16 v[110:113], v[84:87], v[182:185], v[110:113]
	v_mfma_f32_16x16x32_bf16 v[102:105], v[106:109], v[182:185], v[102:105]
	v_mfma_f32_16x16x32_bf16 v[80:83], v[84:87], v[190:193], v[80:83]
	v_mfma_f32_16x16x32_bf16 v[76:79], v[106:109], v[190:193], v[76:79]
	s_setprio 0
	s_setprio 1
	v_mfma_f32_16x16x32_bf16 v[146:149], v[122:125], v[162:165], v[146:149]
	v_mfma_f32_16x16x32_bf16 v[138:141], v[142:145], v[162:165], v[138:141]
	v_mfma_f32_16x16x32_bf16 v[118:121], v[122:125], v[170:173], v[118:121]
	v_mfma_f32_16x16x32_bf16 v[114:117], v[142:145], v[170:173], v[114:117]
	v_mfma_f32_16x16x32_bf16 v[92:95], v[122:125], v[178:181], v[92:95]
	v_mfma_f32_16x16x32_bf16 v[88:91], v[142:145], v[178:181], v[88:91]
	v_mfma_f32_16x16x32_bf16 v[68:71], v[122:125], v[186:189], v[68:71]
	v_mfma_f32_16x16x32_bf16 v[64:67], v[142:145], v[186:189], v[64:67]
	v_mfma_f32_16x16x32_bf16 v[146:149], v[126:129], v[166:169], v[146:149]
	v_mfma_f32_16x16x32_bf16 v[138:141], v[150:153], v[166:169], v[138:141]
	v_mfma_f32_16x16x32_bf16 v[118:121], v[126:129], v[174:177], v[118:121]
	v_mfma_f32_16x16x32_bf16 v[114:117], v[150:153], v[174:177], v[114:117]
	v_mfma_f32_16x16x32_bf16 v[92:95], v[126:129], v[182:185], v[92:95]
	v_mfma_f32_16x16x32_bf16 v[88:91], v[150:153], v[182:185], v[88:91]
	v_mfma_f32_16x16x32_bf16 v[68:71], v[126:129], v[190:193], v[68:71]
	v_mfma_f32_16x16x32_bf16 v[64:67], v[150:153], v[190:193], v[64:67]
	s_setprio 0
	s_barrier
	s_add_i32 s26, s56, s39
	v_lshl_add_u64 v[194:195], v[194:195], 0, s[64:65]
	s_mov_b32 m0, s26
	ds_read_b128 v[162:165], v198 offset:49152
	ds_read_b128 v[166:169], v198 offset:50176
	ds_read_b128 v[170:173], v198 offset:51200
	ds_read_b128 v[174:177], v198 offset:52224
	ds_read_b128 v[178:181], v198 offset:53248
	ds_read_b128 v[182:185], v198 offset:54272
	ds_read_b128 v[186:189], v198 offset:55296
	ds_read_b128 v[190:193], v198 offset:56320
	global_load_lds_dwordx4 v[194:195], off
	s_add_i32 m0, s26, 0x2000
	s_add_u32 s26, s28, 0xb0080
	v_lshl_add_u64 v[194:195], v[196:197], 0, s[64:65]
	s_addc_u32 s27, s29, 0
	s_add_i32 s28, s57, s39
	global_load_lds_dwordx4 v[194:195], off
	v_lshl_add_u64 v[194:195], s[26:27], 0, v[96:97]
	s_mov_b32 m0, s28
	s_nop 0
	global_load_lds_dwordx4 v[194:195], off
	v_lshl_add_u64 v[194:195], s[26:27], 0, v[206:207]
	s_add_i32 m0, s28, 0x2000
	s_nop 0
	global_load_lds_dwordx4 v[194:195], off
	v_lshl_add_u64 v[194:195], v[200:201], 0, s[64:65]
	s_mov_b32 m0, s45
	s_nop 0
	global_load_lds_dwordx4 v[194:195], off
	v_lshl_add_u64 v[194:195], v[212:213], 0, s[64:65]
	s_mov_b32 m0, s46
	s_nop 0
	global_load_lds_dwordx4 v[194:195], off
	s_waitcnt vmcnt(8)
	s_waitcnt lgkmcnt(0)
	s_barrier
	s_setprio 1
	s_waitcnt lgkmcnt(0)
	v_mfma_f32_16x16x32_bf16 v[60:63], v[72:75], v[162:165], v[60:63]
	v_mfma_f32_16x16x32_bf16 v[56:59], v[98:101], v[162:165], v[56:59]
	v_mfma_f32_16x16x32_bf16 v[44:47], v[72:75], v[170:173], v[44:47]
	v_mfma_f32_16x16x32_bf16 v[40:43], v[98:101], v[170:173], v[40:43]
	v_mfma_f32_16x16x32_bf16 v[28:31], v[72:75], v[178:181], v[28:31]
	v_mfma_f32_16x16x32_bf16 v[24:27], v[98:101], v[178:181], v[24:27]
	v_mfma_f32_16x16x32_bf16 v[12:15], v[72:75], v[186:189], v[12:15]
	v_mfma_f32_16x16x32_bf16 v[8:11], v[98:101], v[186:189], v[8:11]
	v_mfma_f32_16x16x32_bf16 v[60:63], v[84:87], v[166:169], v[60:63]
	v_mfma_f32_16x16x32_bf16 v[56:59], v[106:109], v[166:169], v[56:59]
	v_mfma_f32_16x16x32_bf16 v[44:47], v[84:87], v[174:177], v[44:47]
	v_mfma_f32_16x16x32_bf16 v[40:43], v[106:109], v[174:177], v[40:43]
	v_mfma_f32_16x16x32_bf16 v[28:31], v[84:87], v[182:185], v[28:31]
	v_mfma_f32_16x16x32_bf16 v[24:27], v[106:109], v[182:185], v[24:27]
	v_mfma_f32_16x16x32_bf16 v[12:15], v[84:87], v[190:193], v[12:15]
	v_mfma_f32_16x16x32_bf16 v[8:11], v[106:109], v[190:193], v[8:11]
	s_setprio 0
	s_setprio 1
	v_mfma_f32_16x16x32_bf16 v[52:55], v[122:125], v[162:165], v[52:55]
	v_mfma_f32_16x16x32_bf16 v[48:51], v[142:145], v[162:165], v[48:51]
	v_mfma_f32_16x16x32_bf16 v[36:39], v[122:125], v[170:173], v[36:39]
	v_mfma_f32_16x16x32_bf16 v[32:35], v[142:145], v[170:173], v[32:35]
	v_mfma_f32_16x16x32_bf16 v[20:23], v[122:125], v[178:181], v[20:23]
	v_mfma_f32_16x16x32_bf16 v[16:19], v[142:145], v[178:181], v[16:19]
	v_mfma_f32_16x16x32_bf16 v[4:7], v[122:125], v[186:189], v[4:7]
	v_mfma_f32_16x16x32_bf16 v[0:3], v[142:145], v[186:189], v[0:3]
	v_mfma_f32_16x16x32_bf16 v[52:55], v[126:129], v[166:169], v[52:55]
	v_mfma_f32_16x16x32_bf16 v[48:51], v[150:153], v[166:169], v[48:51]
	v_mfma_f32_16x16x32_bf16 v[36:39], v[126:129], v[174:177], v[36:39]
	v_mfma_f32_16x16x32_bf16 v[32:35], v[150:153], v[174:177], v[32:35]
	v_mfma_f32_16x16x32_bf16 v[20:23], v[126:129], v[182:185], v[20:23]
	v_mfma_f32_16x16x32_bf16 v[16:19], v[150:153], v[182:185], v[16:19]
	v_mfma_f32_16x16x32_bf16 v[4:7], v[126:129], v[190:193], v[4:7]
	v_mfma_f32_16x16x32_bf16 v[0:3], v[150:153], v[190:193], v[0:3]
	s_setprio 0
	s_add_i32 s55, s55, 2
	s_add_u32 s53, s53, 0x100
	s_addc_u32 s54, s54, 0
	s_cmp_gt_u32 s55, 41
	s_mov_b64 s[26:27], s[6:7]
	s_barrier
	s_cbranch_scc0 .LBB0_339
	s_and_b64 vcc, exec, s[18:19]
	s_cbranch_vccz .LBB0_342
	s_barrier

.LBB0_461:
	s_add_u32 s30, s28, 0xfffc0080
	s_addc_u32 s31, s29, -1
	s_add_i32 s56, 0, 0x10000
	s_cmp_eq_u32 s55, 12
	s_cselect_b32 s35, s21, s31
	s_cselect_b32 s34, s51, s30
	v_add_u32_e32 v96, s56, v148
	s_cselect_b32 s31, s19, s54
	s_cselect_b32 s30, s52, s53
	s_add_i32 s60, 0, 0x14000
	ds_read_b128 v[144:147], v96
	ds_read_b128 v[154:157], v96 offset:1024
	ds_read_b128 v[158:161], v96 offset:2048
	ds_read_b128 v[162:165], v96 offset:3072
	v_add_u32_e32 v96, s60, v148
	ds_read_b128 v[166:169], v96
	ds_read_b128 v[170:173], v96 offset:1024
	ds_read_b128 v[174:177], v96 offset:2048
	ds_read_b128 v[178:181], v96 offset:3072
	v_lshl_add_u64 v[214:215], s[28:29], 0, v[140:141]
	s_add_i32 m0, s43, 0xc000
	ds_read_b128 v[182:185], v152
	ds_read_b128 v[186:189], v152 offset:1024
	ds_read_b128 v[190:193], v152 offset:2048
	ds_read_b128 v[194:197], v152 offset:3072
	ds_read_b128 v[198:201], v152 offset:4096
	ds_read_b128 v[202:205], v152 offset:5120
	ds_read_b128 v[206:209], v152 offset:6144
	ds_read_b128 v[210:213], v152 offset:7168
	global_load_lds_dwordx4 v[214:215], off
	v_lshl_add_u64 v[214:215], s[28:29], 0, v[142:143]
	s_add_i32 m0, s43, 0xe000
	s_nop 0
	global_load_lds_dwordx4 v[214:215], off
	s_waitcnt vmcnt(8)
	s_waitcnt lgkmcnt(0)
	s_barrier
	s_setprio 1
	s_waitcnt lgkmcnt(0)
	v_mfma_f32_16x16x32_bf16 v[122:125], v[144:147], v[182:185], v[122:125]
	v_mfma_f32_16x16x32_bf16 v[126:129], v[158:161], v[182:185], v[126:129]
	v_mfma_f32_16x16x32_bf16 v[106:109], v[144:147], v[190:193], v[106:109]
	v_mfma_f32_16x16x32_bf16 v[110:113], v[158:161], v[190:193], v[110:113]
	v_mfma_f32_16x16x32_bf16 v[88:91], v[144:147], v[198:201], v[88:91]
	v_mfma_f32_16x16x32_bf16 v[92:95], v[158:161], v[198:201], v[92:95]
	v_mfma_f32_16x16x32_bf16 v[72:75], v[144:147], v[206:209], v[72:75]
	v_mfma_f32_16x16x32_bf16 v[76:79], v[158:161], v[206:209], v[76:79]
	v_mfma_f32_16x16x32_bf16 v[122:125], v[154:157], v[186:189], v[122:125]
	v_mfma_f32_16x16x32_bf16 v[126:129], v[162:165], v[186:189], v[126:129]
	v_mfma_f32_16x16x32_bf16 v[106:109], v[154:157], v[194:197], v[106:109]
	v_mfma_f32_16x16x32_bf16 v[110:113], v[162:165], v[194:197], v[110:113]
	v_mfma_f32_16x16x32_bf16 v[88:91], v[154:157], v[202:205], v[88:91]
	v_mfma_f32_16x16x32_bf16 v[92:95], v[162:165], v[202:205], v[92:95]
	v_mfma_f32_16x16x32_bf16 v[72:75], v[154:157], v[210:213], v[72:75]
	v_mfma_f32_16x16x32_bf16 v[76:79], v[162:165], v[210:213], v[76:79]
	s_setprio 0
	s_setprio 1
	v_mfma_f32_16x16x32_bf16 v[118:121], v[166:169], v[182:185], v[118:121]
	v_mfma_f32_16x16x32_bf16 v[114:117], v[174:177], v[182:185], v[114:117]
	v_mfma_f32_16x16x32_bf16 v[102:105], v[166:169], v[190:193], v[102:105]
	v_mfma_f32_16x16x32_bf16 v[98:101], v[174:177], v[190:193], v[98:101]
	v_mfma_f32_16x16x32_bf16 v[84:87], v[166:169], v[198:201], v[84:87]
	v_mfma_f32_16x16x32_bf16 v[80:83], v[174:177], v[198:201], v[80:83]
	v_mfma_f32_16x16x32_bf16 v[68:71], v[166:169], v[206:209], v[68:71]
	v_mfma_f32_16x16x32_bf16 v[64:67], v[174:177], v[206:209], v[64:67]
	v_mfma_f32_16x16x32_bf16 v[118:121], v[170:173], v[186:189], v[118:121]
	v_mfma_f32_16x16x32_bf16 v[114:117], v[178:181], v[186:189], v[114:117]
	v_mfma_f32_16x16x32_bf16 v[102:105], v[170:173], v[194:197], v[102:105]
	v_mfma_f32_16x16x32_bf16 v[98:101], v[178:181], v[194:197], v[98:101]
	v_mfma_f32_16x16x32_bf16 v[84:87], v[170:173], v[202:205], v[84:87]
	v_mfma_f32_16x16x32_bf16 v[80:83], v[178:181], v[202:205], v[80:83]
	v_mfma_f32_16x16x32_bf16 v[68:71], v[170:173], v[210:213], v[68:71]
	v_mfma_f32_16x16x32_bf16 v[64:67], v[178:181], v[210:213], v[64:67]
	s_setprio 0
	s_barrier
	s_add_i32 s56, s56, s42
	v_lshl_add_u64 v[214:215], s[30:31], 0, v[132:133]
	s_mov_b32 m0, s56
	ds_read_b128 v[182:185], v152 offset:16384
	ds_read_b128 v[186:189], v152 offset:17408
	ds_read_b128 v[190:193], v152 offset:18432
	ds_read_b128 v[194:197], v152 offset:19456
	ds_read_b128 v[198:201], v152 offset:20480
	ds_read_b128 v[202:205], v152 offset:21504
	ds_read_b128 v[206:209], v152 offset:22528
	ds_read_b128 v[210:213], v152 offset:23552
	global_load_lds_dwordx4 v[214:215], off
	s_add_i32 m0, s56, 0x2000
	s_add_u32 s56, s30, 0x40000
	v_lshl_add_u64 v[216:217], s[30:31], 0, v[136:137]
	s_addc_u32 s57, s31, 0
	s_add_i32 s60, s60, s42
	global_load_lds_dwordx4 v[216:217], off
	v_lshl_add_u64 v[218:219], s[56:57], 0, v[132:133]
	s_mov_b32 m0, s60
	v_lshl_add_u64 v[220:221], s[34:35], 0, v[134:135]
	global_load_lds_dwordx4 v[218:219], off
	v_lshl_add_u64 v[218:219], s[56:57], 0, v[136:137]
	s_add_i32 m0, s60, 0x2000
	s_nop 0
	global_load_lds_dwordx4 v[218:219], off
	v_lshl_add_u64 v[218:219], s[34:35], 0, v[130:131]
	s_mov_b32 m0, s43
	s_nop 0
	global_load_lds_dwordx4 v[218:219], off
	s_mov_b32 m0, s44
	s_nop 0
	global_load_lds_dwordx4 v[220:221], off
	s_waitcnt vmcnt(8)
	s_waitcnt lgkmcnt(0)
	s_barrier
	s_setprio 1
	s_waitcnt lgkmcnt(0)
	v_mfma_f32_16x16x32_bf16 v[56:59], v[144:147], v[182:185], v[56:59]
	v_mfma_f32_16x16x32_bf16 v[60:63], v[158:161], v[182:185], v[60:63]
	v_mfma_f32_16x16x32_bf16 v[40:43], v[144:147], v[190:193], v[40:43]
	v_mfma_f32_16x16x32_bf16 v[44:47], v[158:161], v[190:193], v[44:47]
	v_mfma_f32_16x16x32_bf16 v[24:27], v[144:147], v[198:201], v[24:27]
	v_mfma_f32_16x16x32_bf16 v[28:31], v[158:161], v[198:201], v[28:31]
	v_mfma_f32_16x16x32_bf16 v[8:11], v[144:147], v[206:209], v[8:11]
	v_mfma_f32_16x16x32_bf16 v[12:15], v[158:161], v[206:209], v[12:15]
	v_mfma_f32_16x16x32_bf16 v[56:59], v[154:157], v[186:189], v[56:59]
	v_mfma_f32_16x16x32_bf16 v[60:63], v[162:165], v[186:189], v[60:63]
	v_mfma_f32_16x16x32_bf16 v[40:43], v[154:157], v[194:197], v[40:43]
	v_mfma_f32_16x16x32_bf16 v[44:47], v[162:165], v[194:197], v[44:47]
	v_mfma_f32_16x16x32_bf16 v[24:27], v[154:157], v[202:205], v[24:27]
	v_mfma_f32_16x16x32_bf16 v[28:31], v[162:165], v[202:205], v[28:31]
	v_mfma_f32_16x16x32_bf16 v[8:11], v[154:157], v[210:213], v[8:11]
	v_mfma_f32_16x16x32_bf16 v[12:15], v[162:165], v[210:213], v[12:15]
	s_setprio 0
	s_setprio 1
	v_mfma_f32_16x16x32_bf16 v[52:55], v[166:169], v[182:185], v[52:55]
	v_mfma_f32_16x16x32_bf16 v[48:51], v[174:177], v[182:185], v[48:51]
	v_mfma_f32_16x16x32_bf16 v[36:39], v[166:169], v[190:193], v[36:39]
	v_mfma_f32_16x16x32_bf16 v[32:35], v[174:177], v[190:193], v[32:35]
	v_mfma_f32_16x16x32_bf16 v[20:23], v[166:169], v[198:201], v[20:23]
	v_mfma_f32_16x16x32_bf16 v[16:19], v[174:177], v[198:201], v[16:19]
	v_mfma_f32_16x16x32_bf16 v[4:7], v[166:169], v[206:209], v[4:7]
	v_mfma_f32_16x16x32_bf16 v[0:3], v[174:177], v[206:209], v[0:3]
	v_mfma_f32_16x16x32_bf16 v[52:55], v[170:173], v[186:189], v[52:55]
	v_mfma_f32_16x16x32_bf16 v[48:51], v[178:181], v[186:189], v[48:51]
	v_mfma_f32_16x16x32_bf16 v[36:39], v[170:173], v[194:197], v[36:39]
	v_mfma_f32_16x16x32_bf16 v[32:35], v[178:181], v[194:197], v[32:35]
	v_mfma_f32_16x16x32_bf16 v[20:23], v[170:173], v[202:205], v[20:23]
	v_mfma_f32_16x16x32_bf16 v[16:19], v[178:181], v[202:205], v[16:19]
	v_mfma_f32_16x16x32_bf16 v[4:7], v[170:173], v[210:213], v[4:7]
	v_mfma_f32_16x16x32_bf16 v[0:3], v[178:181], v[210:213], v[0:3]
	s_setprio 0
	s_barrier
	s_add_i32 s56, 0, 0x18000
	v_add_u32_e32 v96, s56, v148
	s_add_i32 s57, 0, 0x1c000
	ds_read_b128 v[144:147], v96
	ds_read_b128 v[154:157], v96 offset:1024
	ds_read_b128 v[158:161], v96 offset:2048
	ds_read_b128 v[162:165], v96 offset:3072
	v_add_u32_e32 v96, s57, v148
	ds_read_b128 v[166:169], v96
	ds_read_b128 v[170:173], v96 offset:1024
	ds_read_b128 v[174:177], v96 offset:2048
	ds_read_b128 v[178:181], v96 offset:3072
	s_add_u32 s34, s34, 0x40000
	s_addc_u32 s35, s35, 0
	s_mov_b32 m0, s45
	v_lshl_add_u64 v[222:223], s[34:35], 0, v[130:131]
	ds_read_b128 v[182:185], v152 offset:32768
	ds_read_b128 v[186:189], v152 offset:33792
	ds_read_b128 v[190:193], v152 offset:34816
	ds_read_b128 v[194:197], v152 offset:35840
	ds_read_b128 v[198:201], v152 offset:36864
	ds_read_b128 v[202:205], v152 offset:37888
	ds_read_b128 v[206:209], v152 offset:38912
	ds_read_b128 v[210:213], v152 offset:39936
	global_load_lds_dwordx4 v[222:223], off
	v_lshl_add_u64 v[222:223], s[34:35], 0, v[134:135]
	s_mov_b32 m0, s46
	s_nop 0
	global_load_lds_dwordx4 v[222:223], off
	s_waitcnt vmcnt(8)
	s_waitcnt lgkmcnt(0)
	s_barrier
	s_setprio 1
	s_waitcnt lgkmcnt(0)
	v_mfma_f32_16x16x32_bf16 v[122:125], v[144:147], v[182:185], v[122:125]
	v_mfma_f32_16x16x32_bf16 v[126:129], v[158:161], v[182:185], v[126:129]
	v_mfma_f32_16x16x32_bf16 v[106:109], v[144:147], v[190:193], v[106:109]
	v_mfma_f32_16x16x32_bf16 v[110:113], v[158:161], v[190:193], v[110:113]
	v_mfma_f32_16x16x32_bf16 v[88:91], v[144:147], v[198:201], v[88:91]
	v_mfma_f32_16x16x32_bf16 v[92:95], v[158:161], v[198:201], v[92:95]
	v_mfma_f32_16x16x32_bf16 v[72:75], v[144:147], v[206:209], v[72:75]
	v_mfma_f32_16x16x32_bf16 v[76:79], v[158:161], v[206:209], v[76:79]
	v_mfma_f32_16x16x32_bf16 v[122:125], v[154:157], v[186:189], v[122:125]
	v_mfma_f32_16x16x32_bf16 v[126:129], v[162:165], v[186:189], v[126:129]
	v_mfma_f32_16x16x32_bf16 v[106:109], v[154:157], v[194:197], v[106:109]
	v_mfma_f32_16x16x32_bf16 v[110:113], v[162:165], v[194:197], v[110:113]
	v_mfma_f32_16x16x32_bf16 v[88:91], v[154:157], v[202:205], v[88:91]
	v_mfma_f32_16x16x32_bf16 v[92:95], v[162:165], v[202:205], v[92:95]
	v_mfma_f32_16x16x32_bf16 v[72:75], v[154:157], v[210:213], v[72:75]
	v_mfma_f32_16x16x32_bf16 v[76:79], v[162:165], v[210:213], v[76:79]
	s_setprio 0
	s_setprio 1
	v_mfma_f32_16x16x32_bf16 v[118:121], v[166:169], v[182:185], v[118:121]
	v_mfma_f32_16x16x32_bf16 v[114:117], v[174:177], v[182:185], v[114:117]
	v_mfma_f32_16x16x32_bf16 v[102:105], v[166:169], v[190:193], v[102:105]
	v_mfma_f32_16x16x32_bf16 v[98:101], v[174:177], v[190:193], v[98:101]
	v_mfma_f32_16x16x32_bf16 v[84:87], v[166:169], v[198:201], v[84:87]
	v_mfma_f32_16x16x32_bf16 v[80:83], v[174:177], v[198:201], v[80:83]
	v_mfma_f32_16x16x32_bf16 v[68:71], v[166:169], v[206:209], v[68:71]
	v_mfma_f32_16x16x32_bf16 v[64:67], v[174:177], v[206:209], v[64:67]
	v_mfma_f32_16x16x32_bf16 v[118:121], v[170:173], v[186:189], v[118:121]
	v_mfma_f32_16x16x32_bf16 v[114:117], v[178:181], v[186:189], v[114:117]
	v_mfma_f32_16x16x32_bf16 v[102:105], v[170:173], v[194:197], v[102:105]
	v_mfma_f32_16x16x32_bf16 v[98:101], v[178:181], v[194:197], v[98:101]
	v_mfma_f32_16x16x32_bf16 v[84:87], v[170:173], v[202:205], v[84:87]
	v_mfma_f32_16x16x32_bf16 v[80:83], v[178:181], v[202:205], v[80:83]
	v_mfma_f32_16x16x32_bf16 v[68:71], v[170:173], v[210:213], v[68:71]
	v_mfma_f32_16x16x32_bf16 v[64:67], v[178:181], v[210:213], v[64:67]
	s_setprio 0
	s_barrier
	s_add_i32 s34, s56, s42
	v_lshl_add_u64 v[214:215], v[214:215], 0, s[64:65]
	s_mov_b32 m0, s34
	ds_read_b128 v[182:185], v152 offset:49152
	ds_read_b128 v[186:189], v152 offset:50176
	ds_read_b128 v[190:193], v152 offset:51200
	ds_read_b128 v[194:197], v152 offset:52224
	ds_read_b128 v[198:201], v152 offset:53248
	ds_read_b128 v[202:205], v152 offset:54272
	ds_read_b128 v[206:209], v152 offset:55296
	ds_read_b128 v[210:213], v152 offset:56320
	global_load_lds_dwordx4 v[214:215], off
	s_add_i32 m0, s34, 0x2000
	s_add_u32 s30, s30, 0x40080
	v_lshl_add_u64 v[214:215], v[216:217], 0, s[64:65]
	s_addc_u32 s31, s31, 0
	s_add_i32 s34, s57, s42
	global_load_lds_dwordx4 v[214:215], off
	v_lshl_add_u64 v[214:215], s[30:31], 0, v[132:133]
	s_mov_b32 m0, s34
	s_nop 0
	global_load_lds_dwordx4 v[214:215], off
	v_lshl_add_u64 v[214:215], s[30:31], 0, v[136:137]
	s_add_i32 m0, s34, 0x2000
	s_nop 0
	global_load_lds_dwordx4 v[214:215], off
	v_lshl_add_u64 v[214:215], v[218:219], 0, s[64:65]
	s_mov_b32 m0, s48
	s_nop 0
	global_load_lds_dwordx4 v[214:215], off
	v_lshl_add_u64 v[214:215], v[220:221], 0, s[64:65]
	s_mov_b32 m0, s49
	s_nop 0
	global_load_lds_dwordx4 v[214:215], off
	s_waitcnt vmcnt(8)
	s_waitcnt lgkmcnt(0)
	s_barrier
	s_setprio 1
	s_waitcnt lgkmcnt(0)
	v_mfma_f32_16x16x32_bf16 v[56:59], v[144:147], v[182:185], v[56:59]
	v_mfma_f32_16x16x32_bf16 v[60:63], v[158:161], v[182:185], v[60:63]
	v_mfma_f32_16x16x32_bf16 v[40:43], v[144:147], v[190:193], v[40:43]
	v_mfma_f32_16x16x32_bf16 v[44:47], v[158:161], v[190:193], v[44:47]
	v_mfma_f32_16x16x32_bf16 v[24:27], v[144:147], v[198:201], v[24:27]
	v_mfma_f32_16x16x32_bf16 v[28:31], v[158:161], v[198:201], v[28:31]
	v_mfma_f32_16x16x32_bf16 v[8:11], v[144:147], v[206:209], v[8:11]
	v_mfma_f32_16x16x32_bf16 v[12:15], v[158:161], v[206:209], v[12:15]
	v_mfma_f32_16x16x32_bf16 v[56:59], v[154:157], v[186:189], v[56:59]
	v_mfma_f32_16x16x32_bf16 v[60:63], v[162:165], v[186:189], v[60:63]
	v_mfma_f32_16x16x32_bf16 v[40:43], v[154:157], v[194:197], v[40:43]
	v_mfma_f32_16x16x32_bf16 v[44:47], v[162:165], v[194:197], v[44:47]
	v_mfma_f32_16x16x32_bf16 v[24:27], v[154:157], v[202:205], v[24:27]
	v_mfma_f32_16x16x32_bf16 v[28:31], v[162:165], v[202:205], v[28:31]
	v_mfma_f32_16x16x32_bf16 v[8:11], v[154:157], v[210:213], v[8:11]
	v_mfma_f32_16x16x32_bf16 v[12:15], v[162:165], v[210:213], v[12:15]
	s_setprio 0
	s_setprio 1
	v_mfma_f32_16x16x32_bf16 v[52:55], v[166:169], v[182:185], v[52:55]
	v_mfma_f32_16x16x32_bf16 v[48:51], v[174:177], v[182:185], v[48:51]
	v_mfma_f32_16x16x32_bf16 v[36:39], v[166:169], v[190:193], v[36:39]
	v_mfma_f32_16x16x32_bf16 v[32:35], v[174:177], v[190:193], v[32:35]
	v_mfma_f32_16x16x32_bf16 v[20:23], v[166:169], v[198:201], v[20:23]
	v_mfma_f32_16x16x32_bf16 v[16:19], v[174:177], v[198:201], v[16:19]
	v_mfma_f32_16x16x32_bf16 v[4:7], v[166:169], v[206:209], v[4:7]
	v_mfma_f32_16x16x32_bf16 v[0:3], v[174:177], v[206:209], v[0:3]
	v_mfma_f32_16x16x32_bf16 v[52:55], v[170:173], v[186:189], v[52:55]
	v_mfma_f32_16x16x32_bf16 v[48:51], v[178:181], v[186:189], v[48:51]
	v_mfma_f32_16x16x32_bf16 v[36:39], v[170:173], v[194:197], v[36:39]
	v_mfma_f32_16x16x32_bf16 v[32:35], v[178:181], v[194:197], v[32:35]
	v_mfma_f32_16x16x32_bf16 v[20:23], v[170:173], v[202:205], v[20:23]
	v_mfma_f32_16x16x32_bf16 v[16:19], v[178:181], v[202:205], v[16:19]
	v_mfma_f32_16x16x32_bf16 v[4:7], v[170:173], v[210:213], v[4:7]
	v_mfma_f32_16x16x32_bf16 v[0:3], v[178:181], v[210:213], v[0:3]
	s_setprio 0
	s_add_i32 s55, s55, 2
	s_add_u32 s28, s28, 0x100
	s_addc_u32 s29, s29, 0
	s_add_u32 s53, s53, 0x100
	s_addc_u32 s54, s54, 0
	s_cmp_gt_u32 s55, 13
	s_barrier
	s_cbranch_scc0 .LBB0_461
	s_and_b64 vcc, exec, s[14:15]
	s_cbranch_vccz .LBB0_464
	s_barrier

.LBB0_634:
	s_add_u32 s28, s26, 0xfffc0080
	s_addc_u32 s29, s27, -1
	s_add_i32 s52, 0, 0x10000
	s_cmp_eq_u32 s51, 12
	s_cselect_b32 s31, s17, s29
	s_cselect_b32 s30, s23, s28
	s_cselect_b32 s29, s15, s50
	s_cselect_b32 s28, s25, s49
	s_add_i32 s54, 0, 0x14000
	v_add_u32_e32 v134, s52, v245
	v_add_u32_e32 v150, s54, v245
	ds_read_b128 v[122:125], v134
	ds_read_b128 v[126:129], v134 offset:1024
	ds_read_b128 v[130:133], v134 offset:2048
	ds_read_b128 v[134:137], v134 offset:3072
	ds_read_b128 v[138:141], v150
	ds_read_b128 v[142:145], v150 offset:1024
	ds_read_b128 v[146:149], v150 offset:2048
	ds_read_b128 v[150:153], v150 offset:3072
	v_lshl_add_u64 v[200:201], s[26:27], 0, v[204:205]
	s_add_i32 m0, s40, 0xc000
	ds_read_b128 v[162:165], v199
	ds_read_b128 v[166:169], v199 offset:1024
	ds_read_b128 v[170:173], v199 offset:2048
	ds_read_b128 v[174:177], v199 offset:3072
	ds_read_b128 v[178:181], v199 offset:4096
	ds_read_b128 v[182:185], v199 offset:5120
	ds_read_b128 v[186:189], v199 offset:6144
	ds_read_b128 v[194:197], v199 offset:7168
	global_load_lds_dwordx4 v[200:201], off
	v_lshl_add_u64 v[200:201], s[26:27], 0, v[206:207]
	s_add_i32 m0, s40, 0xe000
	s_nop 0
	global_load_lds_dwordx4 v[200:201], off
	s_waitcnt vmcnt(8)
	s_waitcnt lgkmcnt(0)
	s_barrier
	s_setprio 1
	s_waitcnt lgkmcnt(0)
	v_mfma_f32_16x16x32_bf16 v[158:161], v[122:125], v[162:165], v[158:161]
	v_mfma_f32_16x16x32_bf16 v[154:157], v[130:133], v[162:165], v[154:157]
	v_mfma_f32_16x16x32_bf16 v[110:113], v[122:125], v[170:173], v[110:113]
	v_mfma_f32_16x16x32_bf16 v[106:109], v[130:133], v[170:173], v[106:109]
	v_mfma_f32_16x16x32_bf16 v[92:95], v[122:125], v[178:181], v[92:95]
	v_mfma_f32_16x16x32_bf16 v[88:91], v[130:133], v[178:181], v[88:91]
	v_mfma_f32_16x16x32_bf16 v[76:79], v[122:125], v[186:189], v[76:79]
	v_mfma_f32_16x16x32_bf16 v[72:75], v[130:133], v[186:189], v[72:75]
	v_mfma_f32_16x16x32_bf16 v[158:161], v[126:129], v[166:169], v[158:161]
	v_mfma_f32_16x16x32_bf16 v[154:157], v[134:137], v[166:169], v[154:157]
	v_mfma_f32_16x16x32_bf16 v[110:113], v[126:129], v[174:177], v[110:113]
	v_mfma_f32_16x16x32_bf16 v[106:109], v[134:137], v[174:177], v[106:109]
	v_mfma_f32_16x16x32_bf16 v[92:95], v[126:129], v[182:185], v[92:95]
	v_mfma_f32_16x16x32_bf16 v[88:91], v[134:137], v[182:185], v[88:91]
	v_mfma_f32_16x16x32_bf16 v[76:79], v[126:129], v[194:197], v[76:79]
	v_mfma_f32_16x16x32_bf16 v[72:75], v[134:137], v[194:197], v[72:75]
	s_setprio 0
	s_setprio 1
	v_mfma_f32_16x16x32_bf16 v[118:121], v[138:141], v[162:165], v[118:121]
	v_mfma_f32_16x16x32_bf16 v[114:117], v[146:149], v[162:165], v[114:117]
	v_mfma_f32_16x16x32_bf16 v[102:105], v[138:141], v[170:173], v[102:105]
	v_mfma_f32_16x16x32_bf16 v[98:101], v[146:149], v[170:173], v[98:101]
	v_mfma_f32_16x16x32_bf16 v[84:87], v[138:141], v[178:181], v[84:87]
	v_mfma_f32_16x16x32_bf16 v[80:83], v[146:149], v[178:181], v[80:83]
	v_mfma_f32_16x16x32_bf16 v[68:71], v[138:141], v[186:189], v[68:71]
	v_mfma_f32_16x16x32_bf16 v[64:67], v[146:149], v[186:189], v[64:67]
	v_mfma_f32_16x16x32_bf16 v[118:121], v[142:145], v[166:169], v[118:121]
	v_mfma_f32_16x16x32_bf16 v[114:117], v[150:153], v[166:169], v[114:117]
	v_mfma_f32_16x16x32_bf16 v[102:105], v[142:145], v[174:177], v[102:105]
	v_mfma_f32_16x16x32_bf16 v[98:101], v[150:153], v[174:177], v[98:101]
	v_mfma_f32_16x16x32_bf16 v[84:87], v[142:145], v[182:185], v[84:87]
	v_mfma_f32_16x16x32_bf16 v[80:83], v[150:153], v[182:185], v[80:83]
	v_mfma_f32_16x16x32_bf16 v[68:71], v[142:145], v[194:197], v[68:71]
	v_mfma_f32_16x16x32_bf16 v[64:67], v[150:153], v[194:197], v[64:67]
	s_setprio 0
	s_barrier
	s_add_i32 s52, s52, s39
	v_lshl_add_u64 v[200:201], s[28:29], 0, v[96:97]
	s_mov_b32 m0, s52
	ds_read_b128 v[162:165], v199 offset:16384
	ds_read_b128 v[166:169], v199 offset:17408
	ds_read_b128 v[170:173], v199 offset:18432
	ds_read_b128 v[174:177], v199 offset:19456
	ds_read_b128 v[178:181], v199 offset:20480
	ds_read_b128 v[182:185], v199 offset:21504
	ds_read_b128 v[186:189], v199 offset:22528
	ds_read_b128 v[194:197], v199 offset:23552
	global_load_lds_dwordx4 v[200:201], off
	s_add_i32 m0, s52, 0x2000
	s_add_u32 s52, s28, 0x40000
	v_lshl_add_u64 v[208:209], s[28:29], 0, v[202:203]
	s_addc_u32 s53, s29, 0
	s_add_i32 s54, s54, s39
	global_load_lds_dwordx4 v[208:209], off
	v_lshl_add_u64 v[210:211], s[52:53], 0, v[96:97]
	s_mov_b32 m0, s54
	v_lshl_add_u64 v[212:213], s[30:31], 0, v[192:193]
	global_load_lds_dwordx4 v[210:211], off
	v_lshl_add_u64 v[210:211], s[52:53], 0, v[202:203]
	s_add_i32 m0, s54, 0x2000
	s_nop 0
	global_load_lds_dwordx4 v[210:211], off
	v_lshl_add_u64 v[210:211], s[30:31], 0, v[190:191]
	s_mov_b32 m0, s40
	s_nop 0
	global_load_lds_dwordx4 v[210:211], off
	s_mov_b32 m0, s41
	s_nop 0
	global_load_lds_dwordx4 v[212:213], off
	s_waitcnt vmcnt(8)
	s_waitcnt lgkmcnt(0)
	s_barrier
	s_setprio 1
	s_waitcnt lgkmcnt(0)
	v_mfma_f32_16x16x32_bf16 v[60:63], v[122:125], v[162:165], v[60:63]
	v_mfma_f32_16x16x32_bf16 v[56:59], v[130:133], v[162:165], v[56:59]
	v_mfma_f32_16x16x32_bf16 v[44:47], v[122:125], v[170:173], v[44:47]
	v_mfma_f32_16x16x32_bf16 v[40:43], v[130:133], v[170:173], v[40:43]
	v_mfma_f32_16x16x32_bf16 v[28:31], v[122:125], v[178:181], v[28:31]
	v_mfma_f32_16x16x32_bf16 v[24:27], v[130:133], v[178:181], v[24:27]
	v_mfma_f32_16x16x32_bf16 v[12:15], v[122:125], v[186:189], v[12:15]
	v_mfma_f32_16x16x32_bf16 v[8:11], v[130:133], v[186:189], v[8:11]
	v_mfma_f32_16x16x32_bf16 v[60:63], v[126:129], v[166:169], v[60:63]
	v_mfma_f32_16x16x32_bf16 v[56:59], v[134:137], v[166:169], v[56:59]
	v_mfma_f32_16x16x32_bf16 v[44:47], v[126:129], v[174:177], v[44:47]
	v_mfma_f32_16x16x32_bf16 v[40:43], v[134:137], v[174:177], v[40:43]
	v_mfma_f32_16x16x32_bf16 v[28:31], v[126:129], v[182:185], v[28:31]
	v_mfma_f32_16x16x32_bf16 v[24:27], v[134:137], v[182:185], v[24:27]
	v_mfma_f32_16x16x32_bf16 v[12:15], v[126:129], v[194:197], v[12:15]
	v_mfma_f32_16x16x32_bf16 v[8:11], v[134:137], v[194:197], v[8:11]
	s_setprio 0
	s_setprio 1
	v_mfma_f32_16x16x32_bf16 v[52:55], v[138:141], v[162:165], v[52:55]
	v_mfma_f32_16x16x32_bf16 v[48:51], v[146:149], v[162:165], v[48:51]
	v_mfma_f32_16x16x32_bf16 v[36:39], v[138:141], v[170:173], v[36:39]
	v_mfma_f32_16x16x32_bf16 v[32:35], v[146:149], v[170:173], v[32:35]
	v_mfma_f32_16x16x32_bf16 v[20:23], v[138:141], v[178:181], v[20:23]
	v_mfma_f32_16x16x32_bf16 v[16:19], v[146:149], v[178:181], v[16:19]
	v_mfma_f32_16x16x32_bf16 v[4:7], v[138:141], v[186:189], v[4:7]
	v_mfma_f32_16x16x32_bf16 v[0:3], v[146:149], v[186:189], v[0:3]
	v_mfma_f32_16x16x32_bf16 v[52:55], v[142:145], v[166:169], v[52:55]
	v_mfma_f32_16x16x32_bf16 v[48:51], v[150:153], v[166:169], v[48:51]
	v_mfma_f32_16x16x32_bf16 v[36:39], v[142:145], v[174:177], v[36:39]
	v_mfma_f32_16x16x32_bf16 v[32:35], v[150:153], v[174:177], v[32:35]
	v_mfma_f32_16x16x32_bf16 v[20:23], v[142:145], v[182:185], v[20:23]
	v_mfma_f32_16x16x32_bf16 v[16:19], v[150:153], v[182:185], v[16:19]
	v_mfma_f32_16x16x32_bf16 v[4:7], v[142:145], v[194:197], v[4:7]
	v_mfma_f32_16x16x32_bf16 v[0:3], v[150:153], v[194:197], v[0:3]
	s_setprio 0
	s_barrier
	s_add_i32 s52, 0, 0x18000
	s_add_i32 s53, 0, 0x1c000
	v_add_u32_e32 v134, s52, v245
	v_add_u32_e32 v150, s53, v245
	ds_read_b128 v[122:125], v134
	ds_read_b128 v[126:129], v134 offset:1024
	ds_read_b128 v[130:133], v134 offset:2048
	ds_read_b128 v[134:137], v134 offset:3072
	ds_read_b128 v[138:141], v150
	ds_read_b128 v[142:145], v150 offset:1024
	ds_read_b128 v[146:149], v150 offset:2048
	ds_read_b128 v[150:153], v150 offset:3072
	s_add_u32 s30, s30, 0x40000
	s_addc_u32 s31, s31, 0
	s_mov_b32 m0, s42
	v_lshl_add_u64 v[214:215], s[30:31], 0, v[190:191]
	ds_read_b128 v[162:165], v199 offset:32768
	ds_read_b128 v[166:169], v199 offset:33792
	ds_read_b128 v[170:173], v199 offset:34816
	ds_read_b128 v[174:177], v199 offset:35840
	ds_read_b128 v[178:181], v199 offset:36864
	ds_read_b128 v[182:185], v199 offset:37888
	ds_read_b128 v[186:189], v199 offset:38912
	ds_read_b128 v[194:197], v199 offset:39936
	global_load_lds_dwordx4 v[214:215], off
	v_lshl_add_u64 v[214:215], s[30:31], 0, v[192:193]
	s_mov_b32 m0, s43
	s_nop 0
	global_load_lds_dwordx4 v[214:215], off
	s_waitcnt vmcnt(8)
	s_waitcnt lgkmcnt(0)
	s_barrier
	s_setprio 1
	s_waitcnt lgkmcnt(0)
	v_mfma_f32_16x16x32_bf16 v[158:161], v[122:125], v[162:165], v[158:161]
	v_mfma_f32_16x16x32_bf16 v[154:157], v[130:133], v[162:165], v[154:157]
	v_mfma_f32_16x16x32_bf16 v[110:113], v[122:125], v[170:173], v[110:113]
	v_mfma_f32_16x16x32_bf16 v[106:109], v[130:133], v[170:173], v[106:109]
	v_mfma_f32_16x16x32_bf16 v[92:95], v[122:125], v[178:181], v[92:95]
	v_mfma_f32_16x16x32_bf16 v[88:91], v[130:133], v[178:181], v[88:91]
	v_mfma_f32_16x16x32_bf16 v[76:79], v[122:125], v[186:189], v[76:79]
	v_mfma_f32_16x16x32_bf16 v[72:75], v[130:133], v[186:189], v[72:75]
	v_mfma_f32_16x16x32_bf16 v[158:161], v[126:129], v[166:169], v[158:161]
	v_mfma_f32_16x16x32_bf16 v[154:157], v[134:137], v[166:169], v[154:157]
	v_mfma_f32_16x16x32_bf16 v[110:113], v[126:129], v[174:177], v[110:113]
	v_mfma_f32_16x16x32_bf16 v[106:109], v[134:137], v[174:177], v[106:109]
	v_mfma_f32_16x16x32_bf16 v[92:95], v[126:129], v[182:185], v[92:95]
	v_mfma_f32_16x16x32_bf16 v[88:91], v[134:137], v[182:185], v[88:91]
	v_mfma_f32_16x16x32_bf16 v[76:79], v[126:129], v[194:197], v[76:79]
	v_mfma_f32_16x16x32_bf16 v[72:75], v[134:137], v[194:197], v[72:75]
	s_setprio 0
	s_setprio 1
	v_mfma_f32_16x16x32_bf16 v[118:121], v[138:141], v[162:165], v[118:121]
	v_mfma_f32_16x16x32_bf16 v[114:117], v[146:149], v[162:165], v[114:117]
	v_mfma_f32_16x16x32_bf16 v[102:105], v[138:141], v[170:173], v[102:105]
	v_mfma_f32_16x16x32_bf16 v[98:101], v[146:149], v[170:173], v[98:101]
	v_mfma_f32_16x16x32_bf16 v[84:87], v[138:141], v[178:181], v[84:87]
	v_mfma_f32_16x16x32_bf16 v[80:83], v[146:149], v[178:181], v[80:83]
	v_mfma_f32_16x16x32_bf16 v[68:71], v[138:141], v[186:189], v[68:71]
	v_mfma_f32_16x16x32_bf16 v[64:67], v[146:149], v[186:189], v[64:67]
	v_mfma_f32_16x16x32_bf16 v[118:121], v[142:145], v[166:169], v[118:121]
	v_mfma_f32_16x16x32_bf16 v[114:117], v[150:153], v[166:169], v[114:117]
	v_mfma_f32_16x16x32_bf16 v[102:105], v[142:145], v[174:177], v[102:105]
	v_mfma_f32_16x16x32_bf16 v[98:101], v[150:153], v[174:177], v[98:101]
	v_mfma_f32_16x16x32_bf16 v[84:87], v[142:145], v[182:185], v[84:87]
	v_mfma_f32_16x16x32_bf16 v[80:83], v[150:153], v[182:185], v[80:83]
	v_mfma_f32_16x16x32_bf16 v[68:71], v[142:145], v[194:197], v[68:71]
	v_mfma_f32_16x16x32_bf16 v[64:67], v[150:153], v[194:197], v[64:67]
	s_setprio 0
	s_barrier
	s_add_i32 s30, s52, s39
	v_lshl_add_u64 v[200:201], v[200:201], 0, s[64:65]
	s_mov_b32 m0, s30
	ds_read_b128 v[162:165], v199 offset:49152
	ds_read_b128 v[166:169], v199 offset:50176
	ds_read_b128 v[170:173], v199 offset:51200
	ds_read_b128 v[174:177], v199 offset:52224
	ds_read_b128 v[178:181], v199 offset:53248
	ds_read_b128 v[182:185], v199 offset:54272
	ds_read_b128 v[186:189], v199 offset:55296
	ds_read_b128 v[194:197], v199 offset:56320
	global_load_lds_dwordx4 v[200:201], off
	s_add_i32 m0, s30, 0x2000
	s_add_u32 s28, s28, 0x40080
	v_lshl_add_u64 v[200:201], v[208:209], 0, s[64:65]
	s_addc_u32 s29, s29, 0
	s_add_i32 s30, s53, s39
	global_load_lds_dwordx4 v[200:201], off
	v_lshl_add_u64 v[200:201], s[28:29], 0, v[96:97]
	s_mov_b32 m0, s30
	s_nop 0
	global_load_lds_dwordx4 v[200:201], off
	v_lshl_add_u64 v[200:201], s[28:29], 0, v[202:203]
	s_add_i32 m0, s30, 0x2000
	s_nop 0
	global_load_lds_dwordx4 v[200:201], off
	v_lshl_add_u64 v[200:201], v[210:211], 0, s[64:65]
	s_mov_b32 m0, s45
	s_nop 0
	global_load_lds_dwordx4 v[200:201], off
	v_lshl_add_u64 v[200:201], v[212:213], 0, s[64:65]
	s_mov_b32 m0, s46
	s_nop 0
	global_load_lds_dwordx4 v[200:201], off
	s_waitcnt vmcnt(8)
	s_waitcnt lgkmcnt(0)
	s_barrier
	s_setprio 1
	s_waitcnt lgkmcnt(0)
	v_mfma_f32_16x16x32_bf16 v[60:63], v[122:125], v[162:165], v[60:63]
	v_mfma_f32_16x16x32_bf16 v[56:59], v[130:133], v[162:165], v[56:59]
	v_mfma_f32_16x16x32_bf16 v[44:47], v[122:125], v[170:173], v[44:47]
	v_mfma_f32_16x16x32_bf16 v[40:43], v[130:133], v[170:173], v[40:43]
	v_mfma_f32_16x16x32_bf16 v[28:31], v[122:125], v[178:181], v[28:31]
	v_mfma_f32_16x16x32_bf16 v[24:27], v[130:133], v[178:181], v[24:27]
	v_mfma_f32_16x16x32_bf16 v[12:15], v[122:125], v[186:189], v[12:15]
	v_mfma_f32_16x16x32_bf16 v[8:11], v[130:133], v[186:189], v[8:11]
	v_mfma_f32_16x16x32_bf16 v[60:63], v[126:129], v[166:169], v[60:63]
	v_mfma_f32_16x16x32_bf16 v[56:59], v[134:137], v[166:169], v[56:59]
	v_mfma_f32_16x16x32_bf16 v[44:47], v[126:129], v[174:177], v[44:47]
	v_mfma_f32_16x16x32_bf16 v[40:43], v[134:137], v[174:177], v[40:43]
	v_mfma_f32_16x16x32_bf16 v[28:31], v[126:129], v[182:185], v[28:31]
	v_mfma_f32_16x16x32_bf16 v[24:27], v[134:137], v[182:185], v[24:27]
	v_mfma_f32_16x16x32_bf16 v[12:15], v[126:129], v[194:197], v[12:15]
	v_mfma_f32_16x16x32_bf16 v[8:11], v[134:137], v[194:197], v[8:11]
	s_setprio 0
	s_setprio 1
	v_mfma_f32_16x16x32_bf16 v[52:55], v[138:141], v[162:165], v[52:55]
	v_mfma_f32_16x16x32_bf16 v[48:51], v[146:149], v[162:165], v[48:51]
	v_mfma_f32_16x16x32_bf16 v[36:39], v[138:141], v[170:173], v[36:39]
	v_mfma_f32_16x16x32_bf16 v[32:35], v[146:149], v[170:173], v[32:35]
	v_mfma_f32_16x16x32_bf16 v[20:23], v[138:141], v[178:181], v[20:23]
	v_mfma_f32_16x16x32_bf16 v[16:19], v[146:149], v[178:181], v[16:19]
	v_mfma_f32_16x16x32_bf16 v[4:7], v[138:141], v[186:189], v[4:7]
	v_mfma_f32_16x16x32_bf16 v[0:3], v[146:149], v[186:189], v[0:3]
	v_mfma_f32_16x16x32_bf16 v[52:55], v[142:145], v[166:169], v[52:55]
	v_mfma_f32_16x16x32_bf16 v[48:51], v[150:153], v[166:169], v[48:51]
	v_mfma_f32_16x16x32_bf16 v[36:39], v[142:145], v[174:177], v[36:39]
	v_mfma_f32_16x16x32_bf16 v[32:35], v[150:153], v[174:177], v[32:35]
	v_mfma_f32_16x16x32_bf16 v[20:23], v[142:145], v[182:185], v[20:23]
	v_mfma_f32_16x16x32_bf16 v[16:19], v[150:153], v[182:185], v[16:19]
	v_mfma_f32_16x16x32_bf16 v[4:7], v[142:145], v[194:197], v[4:7]
	v_mfma_f32_16x16x32_bf16 v[0:3], v[150:153], v[194:197], v[0:3]
	s_setprio 0
	s_add_i32 s51, s51, 2
	s_add_u32 s26, s26, 0x100
	s_addc_u32 s27, s27, 0
	s_add_u32 s49, s49, 0x100
	s_addc_u32 s50, s50, 0
	s_cmp_gt_u32 s51, 13
	s_barrier
	s_cbranch_scc0 .LBB0_634
	s_and_b64 vcc, exec, s[12:13]
	s_cbranch_vccz .LBB0_637
	s_barrier

.LBB0_722:
	s_add_u32 s26, s24, 0xfffc0080
	s_addc_u32 s27, s25, -1
	s_add_i32 s53, 0, 0x10000
	s_cmp_eq_u32 s52, 12
	s_cselect_b32 s29, s17, s27
	s_cselect_b32 s28, s48, s26
	v_add_u32_e32 v147, s53, v141
	s_cselect_b32 s27, s15, s51
	s_cselect_b32 s26, s49, s50
	s_add_i32 s56, 0, 0x14000
	ds_read_b128 v[148:151], v147
	ds_read_b128 v[152:155], v147 offset:1024
	ds_read_b128 v[156:159], v147 offset:2048
	ds_read_b128 v[160:163], v147 offset:3072
	v_add_u32_e32 v147, s56, v141
	ds_read_b128 v[164:167], v147
	ds_read_b128 v[168:171], v147 offset:1024
	ds_read_b128 v[172:175], v147 offset:2048
	ds_read_b128 v[176:179], v147 offset:3072
	v_lshl_add_u64 v[192:193], s[24:25], 0, v[136:137]
	s_add_i32 m0, s23, 0xc000
	ds_read_b128 v[180:183], v146
	ds_read_b128 v[184:187], v146 offset:1024
	ds_read_b128 v[188:191], v146 offset:2048
	ds_read_b128 v[202:205], v146 offset:3072
	ds_read_b128 v[206:209], v146 offset:4096
	ds_read_b128 v[210:213], v146 offset:5120
	ds_read_b128 v[214:217], v146 offset:6144
	ds_read_b128 v[218:221], v146 offset:7168
	global_load_lds_dwordx4 v[192:193], off
	v_lshl_add_u64 v[192:193], s[24:25], 0, v[138:139]
	s_add_i32 m0, s23, 0xe000
	s_nop 0
	global_load_lds_dwordx4 v[192:193], off
	s_waitcnt vmcnt(8)
	s_waitcnt lgkmcnt(0)
	s_barrier
	s_setprio 1
	s_waitcnt lgkmcnt(0)
	v_mfma_f32_16x16x32_bf16 v[126:129], v[148:151], v[180:183], v[126:129]
	v_mfma_f32_16x16x32_bf16 v[122:125], v[156:159], v[180:183], v[122:125]
	v_mfma_f32_16x16x32_bf16 v[114:117], v[148:151], v[188:191], v[114:117]
	v_mfma_f32_16x16x32_bf16 v[106:109], v[156:159], v[188:191], v[106:109]
	v_mfma_f32_16x16x32_bf16 v[98:101], v[148:151], v[206:209], v[98:101]
	v_mfma_f32_16x16x32_bf16 v[88:91], v[156:159], v[206:209], v[88:91]
	v_mfma_f32_16x16x32_bf16 v[80:83], v[148:151], v[214:217], v[80:83]
	v_mfma_f32_16x16x32_bf16 v[72:75], v[156:159], v[214:217], v[72:75]
	v_mfma_f32_16x16x32_bf16 v[126:129], v[152:155], v[184:187], v[126:129]
	v_mfma_f32_16x16x32_bf16 v[122:125], v[160:163], v[184:187], v[122:125]
	v_mfma_f32_16x16x32_bf16 v[114:117], v[152:155], v[202:205], v[114:117]
	v_mfma_f32_16x16x32_bf16 v[106:109], v[160:163], v[202:205], v[106:109]
	v_mfma_f32_16x16x32_bf16 v[98:101], v[152:155], v[210:213], v[98:101]
	v_mfma_f32_16x16x32_bf16 v[88:91], v[160:163], v[210:213], v[88:91]
	v_mfma_f32_16x16x32_bf16 v[80:83], v[152:155], v[218:221], v[80:83]
	v_mfma_f32_16x16x32_bf16 v[72:75], v[160:163], v[218:221], v[72:75]
	s_setprio 0
	s_setprio 1
	v_mfma_f32_16x16x32_bf16 v[118:121], v[164:167], v[180:183], v[118:121]
	v_mfma_f32_16x16x32_bf16 v[110:113], v[172:175], v[180:183], v[110:113]
	v_mfma_f32_16x16x32_bf16 v[102:105], v[164:167], v[188:191], v[102:105]
	v_mfma_f32_16x16x32_bf16 v[92:95], v[172:175], v[188:191], v[92:95]
	v_mfma_f32_16x16x32_bf16 v[84:87], v[164:167], v[206:209], v[84:87]
	v_mfma_f32_16x16x32_bf16 v[76:79], v[172:175], v[206:209], v[76:79]
	v_mfma_f32_16x16x32_bf16 v[68:71], v[164:167], v[214:217], v[68:71]
	v_mfma_f32_16x16x32_bf16 v[64:67], v[172:175], v[214:217], v[64:67]
	v_mfma_f32_16x16x32_bf16 v[118:121], v[168:171], v[184:187], v[118:121]
	v_mfma_f32_16x16x32_bf16 v[110:113], v[176:179], v[184:187], v[110:113]
	v_mfma_f32_16x16x32_bf16 v[102:105], v[168:171], v[202:205], v[102:105]
	v_mfma_f32_16x16x32_bf16 v[92:95], v[176:179], v[202:205], v[92:95]
	v_mfma_f32_16x16x32_bf16 v[84:87], v[168:171], v[210:213], v[84:87]
	v_mfma_f32_16x16x32_bf16 v[76:79], v[176:179], v[210:213], v[76:79]
	v_mfma_f32_16x16x32_bf16 v[68:71], v[168:171], v[218:221], v[68:71]
	v_mfma_f32_16x16x32_bf16 v[64:67], v[176:179], v[218:221], v[64:67]
	s_setprio 0
	s_barrier
	s_add_i32 s53, s53, s38
	v_lshl_add_u64 v[192:193], s[26:27], 0, v[96:97]
	s_mov_b32 m0, s53
	ds_read_b128 v[180:183], v146 offset:16384
	ds_read_b128 v[184:187], v146 offset:17408
	ds_read_b128 v[188:191], v146 offset:18432
	ds_read_b128 v[202:205], v146 offset:19456
	ds_read_b128 v[206:209], v146 offset:20480
	ds_read_b128 v[210:213], v146 offset:21504
	ds_read_b128 v[214:217], v146 offset:22528
	ds_read_b128 v[218:221], v146 offset:23552
	global_load_lds_dwordx4 v[192:193], off
	s_add_i32 m0, s53, 0x2000
	s_add_u32 s54, s26, 0x40000
	v_lshl_add_u64 v[194:195], s[26:27], 0, v[130:131]
	s_addc_u32 s55, s27, 0
	s_add_i32 s53, s56, s38
	global_load_lds_dwordx4 v[194:195], off
	v_lshl_add_u64 v[196:197], s[54:55], 0, v[96:97]
	s_mov_b32 m0, s53
	v_lshl_add_u64 v[198:199], s[28:29], 0, v[132:133]
	global_load_lds_dwordx4 v[196:197], off
	v_lshl_add_u64 v[196:197], s[54:55], 0, v[130:131]
	s_add_i32 m0, s53, 0x2000
	s_nop 0
	global_load_lds_dwordx4 v[196:197], off
	v_lshl_add_u64 v[196:197], s[28:29], 0, v[134:135]
	s_mov_b32 m0, s23
	s_nop 0
	global_load_lds_dwordx4 v[196:197], off
	s_mov_b32 m0, s39
	s_nop 0
	global_load_lds_dwordx4 v[198:199], off
	s_waitcnt vmcnt(8)
	s_waitcnt lgkmcnt(0)
	s_barrier
	s_setprio 1
	s_waitcnt lgkmcnt(0)
	v_mfma_f32_16x16x32_bf16 v[60:63], v[148:151], v[180:183], v[60:63]
	v_mfma_f32_16x16x32_bf16 v[56:59], v[156:159], v[180:183], v[56:59]
	v_mfma_f32_16x16x32_bf16 v[48:51], v[148:151], v[188:191], v[48:51]
	v_mfma_f32_16x16x32_bf16 v[40:43], v[156:159], v[188:191], v[40:43]
	v_mfma_f32_16x16x32_bf16 v[32:35], v[148:151], v[206:209], v[32:35]
	v_mfma_f32_16x16x32_bf16 v[24:27], v[156:159], v[206:209], v[24:27]
	v_mfma_f32_16x16x32_bf16 v[16:19], v[148:151], v[214:217], v[16:19]
	v_mfma_f32_16x16x32_bf16 v[8:11], v[156:159], v[214:217], v[8:11]
	v_mfma_f32_16x16x32_bf16 v[60:63], v[152:155], v[184:187], v[60:63]
	v_mfma_f32_16x16x32_bf16 v[56:59], v[160:163], v[184:187], v[56:59]
	v_mfma_f32_16x16x32_bf16 v[48:51], v[152:155], v[202:205], v[48:51]
	v_mfma_f32_16x16x32_bf16 v[40:43], v[160:163], v[202:205], v[40:43]
	v_mfma_f32_16x16x32_bf16 v[32:35], v[152:155], v[210:213], v[32:35]
	v_mfma_f32_16x16x32_bf16 v[24:27], v[160:163], v[210:213], v[24:27]
	v_mfma_f32_16x16x32_bf16 v[16:19], v[152:155], v[218:221], v[16:19]
	v_mfma_f32_16x16x32_bf16 v[8:11], v[160:163], v[218:221], v[8:11]
	s_setprio 0
	s_setprio 1
	v_mfma_f32_16x16x32_bf16 v[52:55], v[164:167], v[180:183], v[52:55]
	v_mfma_f32_16x16x32_bf16 v[44:47], v[172:175], v[180:183], v[44:47]
	v_mfma_f32_16x16x32_bf16 v[36:39], v[164:167], v[188:191], v[36:39]
	v_mfma_f32_16x16x32_bf16 v[28:31], v[172:175], v[188:191], v[28:31]
	v_mfma_f32_16x16x32_bf16 v[20:23], v[164:167], v[206:209], v[20:23]
	v_mfma_f32_16x16x32_bf16 v[12:15], v[172:175], v[206:209], v[12:15]
	v_mfma_f32_16x16x32_bf16 v[4:7], v[164:167], v[214:217], v[4:7]
	v_mfma_f32_16x16x32_bf16 v[0:3], v[172:175], v[214:217], v[0:3]
	v_mfma_f32_16x16x32_bf16 v[52:55], v[168:171], v[184:187], v[52:55]
	v_mfma_f32_16x16x32_bf16 v[44:47], v[176:179], v[184:187], v[44:47]
	v_mfma_f32_16x16x32_bf16 v[36:39], v[168:171], v[202:205], v[36:39]
	v_mfma_f32_16x16x32_bf16 v[28:31], v[176:179], v[202:205], v[28:31]
	v_mfma_f32_16x16x32_bf16 v[20:23], v[168:171], v[210:213], v[20:23]
	v_mfma_f32_16x16x32_bf16 v[12:15], v[176:179], v[210:213], v[12:15]
	v_mfma_f32_16x16x32_bf16 v[4:7], v[168:171], v[218:221], v[4:7]
	v_mfma_f32_16x16x32_bf16 v[0:3], v[176:179], v[218:221], v[0:3]
	s_setprio 0
	s_barrier
	s_add_i32 s53, 0, 0x18000
	v_add_u32_e32 v147, s53, v141
	s_add_i32 s54, 0, 0x1c000
	ds_read_b128 v[148:151], v147
	ds_read_b128 v[152:155], v147 offset:1024
	ds_read_b128 v[156:159], v147 offset:2048
	ds_read_b128 v[160:163], v147 offset:3072
	v_add_u32_e32 v147, s54, v141
	ds_read_b128 v[164:167], v147
	ds_read_b128 v[168:171], v147 offset:1024
	ds_read_b128 v[172:175], v147 offset:2048
	ds_read_b128 v[176:179], v147 offset:3072
	s_add_u32 s28, s28, 0x40000
	s_addc_u32 s29, s29, 0
	s_mov_b32 m0, s40
	v_lshl_add_u64 v[200:201], s[28:29], 0, v[134:135]
	ds_read_b128 v[180:183], v146 offset:32768
	ds_read_b128 v[184:187], v146 offset:33792
	ds_read_b128 v[188:191], v146 offset:34816
	ds_read_b128 v[202:205], v146 offset:35840
	ds_read_b128 v[206:209], v146 offset:36864
	ds_read_b128 v[210:213], v146 offset:37888
	ds_read_b128 v[214:217], v146 offset:38912
	ds_read_b128 v[218:221], v146 offset:39936
	global_load_lds_dwordx4 v[200:201], off
	v_lshl_add_u64 v[200:201], s[28:29], 0, v[132:133]
	s_mov_b32 m0, s41
	s_nop 0
	global_load_lds_dwordx4 v[200:201], off
	s_waitcnt vmcnt(8)
	s_waitcnt lgkmcnt(0)
	s_barrier
	s_setprio 1
	s_waitcnt lgkmcnt(0)
	v_mfma_f32_16x16x32_bf16 v[126:129], v[148:151], v[180:183], v[126:129]
	v_mfma_f32_16x16x32_bf16 v[122:125], v[156:159], v[180:183], v[122:125]
	v_mfma_f32_16x16x32_bf16 v[114:117], v[148:151], v[188:191], v[114:117]
	v_mfma_f32_16x16x32_bf16 v[106:109], v[156:159], v[188:191], v[106:109]
	v_mfma_f32_16x16x32_bf16 v[98:101], v[148:151], v[206:209], v[98:101]
	v_mfma_f32_16x16x32_bf16 v[88:91], v[156:159], v[206:209], v[88:91]
	v_mfma_f32_16x16x32_bf16 v[80:83], v[148:151], v[214:217], v[80:83]
	v_mfma_f32_16x16x32_bf16 v[72:75], v[156:159], v[214:217], v[72:75]
	v_mfma_f32_16x16x32_bf16 v[126:129], v[152:155], v[184:187], v[126:129]
	v_mfma_f32_16x16x32_bf16 v[122:125], v[160:163], v[184:187], v[122:125]
	v_mfma_f32_16x16x32_bf16 v[114:117], v[152:155], v[202:205], v[114:117]
	v_mfma_f32_16x16x32_bf16 v[106:109], v[160:163], v[202:205], v[106:109]
	v_mfma_f32_16x16x32_bf16 v[98:101], v[152:155], v[210:213], v[98:101]
	v_mfma_f32_16x16x32_bf16 v[88:91], v[160:163], v[210:213], v[88:91]
	v_mfma_f32_16x16x32_bf16 v[80:83], v[152:155], v[218:221], v[80:83]
	v_mfma_f32_16x16x32_bf16 v[72:75], v[160:163], v[218:221], v[72:75]
	s_setprio 0
	s_setprio 1
	v_mfma_f32_16x16x32_bf16 v[118:121], v[164:167], v[180:183], v[118:121]
	v_mfma_f32_16x16x32_bf16 v[110:113], v[172:175], v[180:183], v[110:113]
	v_mfma_f32_16x16x32_bf16 v[102:105], v[164:167], v[188:191], v[102:105]
	v_mfma_f32_16x16x32_bf16 v[92:95], v[172:175], v[188:191], v[92:95]
	v_mfma_f32_16x16x32_bf16 v[84:87], v[164:167], v[206:209], v[84:87]
	v_mfma_f32_16x16x32_bf16 v[76:79], v[172:175], v[206:209], v[76:79]
	v_mfma_f32_16x16x32_bf16 v[68:71], v[164:167], v[214:217], v[68:71]
	v_mfma_f32_16x16x32_bf16 v[64:67], v[172:175], v[214:217], v[64:67]
	v_mfma_f32_16x16x32_bf16 v[118:121], v[168:171], v[184:187], v[118:121]
	v_mfma_f32_16x16x32_bf16 v[110:113], v[176:179], v[184:187], v[110:113]
	v_mfma_f32_16x16x32_bf16 v[102:105], v[168:171], v[202:205], v[102:105]
	v_mfma_f32_16x16x32_bf16 v[92:95], v[176:179], v[202:205], v[92:95]
	v_mfma_f32_16x16x32_bf16 v[84:87], v[168:171], v[210:213], v[84:87]
	v_mfma_f32_16x16x32_bf16 v[76:79], v[176:179], v[210:213], v[76:79]
	v_mfma_f32_16x16x32_bf16 v[68:71], v[168:171], v[218:221], v[68:71]
	v_mfma_f32_16x16x32_bf16 v[64:67], v[176:179], v[218:221], v[64:67]
	s_setprio 0
	s_barrier
	s_add_i32 s28, s53, s38
	v_lshl_add_u64 v[192:193], v[192:193], 0, s[64:65]
	s_mov_b32 m0, s28
	ds_read_b128 v[180:183], v146 offset:49152
	ds_read_b128 v[184:187], v146 offset:50176
	ds_read_b128 v[188:191], v146 offset:51200
	ds_read_b128 v[202:205], v146 offset:52224
	ds_read_b128 v[206:209], v146 offset:53248
	ds_read_b128 v[210:213], v146 offset:54272
	ds_read_b128 v[214:217], v146 offset:55296
	ds_read_b128 v[218:221], v146 offset:56320
	global_load_lds_dwordx4 v[192:193], off
	s_add_i32 m0, s28, 0x2000
	s_add_u32 s26, s26, 0x40080
	v_lshl_add_u64 v[192:193], v[194:195], 0, s[64:65]
	s_addc_u32 s27, s27, 0
	s_add_i32 s28, s54, s38
	global_load_lds_dwordx4 v[192:193], off
	v_lshl_add_u64 v[192:193], s[26:27], 0, v[96:97]
	s_mov_b32 m0, s28
	s_nop 0
	global_load_lds_dwordx4 v[192:193], off
	v_lshl_add_u64 v[192:193], s[26:27], 0, v[130:131]
	s_add_i32 m0, s28, 0x2000
	s_nop 0
	global_load_lds_dwordx4 v[192:193], off
	v_lshl_add_u64 v[192:193], v[196:197], 0, s[64:65]
	s_mov_b32 m0, s42
	s_nop 0
	global_load_lds_dwordx4 v[192:193], off
	v_lshl_add_u64 v[192:193], v[198:199], 0, s[64:65]
	s_mov_b32 m0, s43
	s_nop 0
	global_load_lds_dwordx4 v[192:193], off
	s_waitcnt vmcnt(8)
	s_waitcnt lgkmcnt(0)
	s_barrier
	s_setprio 1
	s_waitcnt lgkmcnt(0)
	v_mfma_f32_16x16x32_bf16 v[60:63], v[148:151], v[180:183], v[60:63]
	v_mfma_f32_16x16x32_bf16 v[56:59], v[156:159], v[180:183], v[56:59]
	v_mfma_f32_16x16x32_bf16 v[48:51], v[148:151], v[188:191], v[48:51]
	v_mfma_f32_16x16x32_bf16 v[40:43], v[156:159], v[188:191], v[40:43]
	v_mfma_f32_16x16x32_bf16 v[32:35], v[148:151], v[206:209], v[32:35]
	v_mfma_f32_16x16x32_bf16 v[24:27], v[156:159], v[206:209], v[24:27]
	v_mfma_f32_16x16x32_bf16 v[16:19], v[148:151], v[214:217], v[16:19]
	v_mfma_f32_16x16x32_bf16 v[8:11], v[156:159], v[214:217], v[8:11]
	v_mfma_f32_16x16x32_bf16 v[60:63], v[152:155], v[184:187], v[60:63]
	v_mfma_f32_16x16x32_bf16 v[56:59], v[160:163], v[184:187], v[56:59]
	v_mfma_f32_16x16x32_bf16 v[48:51], v[152:155], v[202:205], v[48:51]
	v_mfma_f32_16x16x32_bf16 v[40:43], v[160:163], v[202:205], v[40:43]
	v_mfma_f32_16x16x32_bf16 v[32:35], v[152:155], v[210:213], v[32:35]
	v_mfma_f32_16x16x32_bf16 v[24:27], v[160:163], v[210:213], v[24:27]
	v_mfma_f32_16x16x32_bf16 v[16:19], v[152:155], v[218:221], v[16:19]
	v_mfma_f32_16x16x32_bf16 v[8:11], v[160:163], v[218:221], v[8:11]
	s_setprio 0
	s_setprio 1
	v_mfma_f32_16x16x32_bf16 v[52:55], v[164:167], v[180:183], v[52:55]
	v_mfma_f32_16x16x32_bf16 v[44:47], v[172:175], v[180:183], v[44:47]
	v_mfma_f32_16x16x32_bf16 v[36:39], v[164:167], v[188:191], v[36:39]
	v_mfma_f32_16x16x32_bf16 v[28:31], v[172:175], v[188:191], v[28:31]
	v_mfma_f32_16x16x32_bf16 v[20:23], v[164:167], v[206:209], v[20:23]
	v_mfma_f32_16x16x32_bf16 v[12:15], v[172:175], v[206:209], v[12:15]
	v_mfma_f32_16x16x32_bf16 v[4:7], v[164:167], v[214:217], v[4:7]
	v_mfma_f32_16x16x32_bf16 v[0:3], v[172:175], v[214:217], v[0:3]
	v_mfma_f32_16x16x32_bf16 v[52:55], v[168:171], v[184:187], v[52:55]
	v_mfma_f32_16x16x32_bf16 v[44:47], v[176:179], v[184:187], v[44:47]
	v_mfma_f32_16x16x32_bf16 v[36:39], v[168:171], v[202:205], v[36:39]
	v_mfma_f32_16x16x32_bf16 v[28:31], v[176:179], v[202:205], v[28:31]
	v_mfma_f32_16x16x32_bf16 v[20:23], v[168:171], v[210:213], v[20:23]
	v_mfma_f32_16x16x32_bf16 v[12:15], v[176:179], v[210:213], v[12:15]
	v_mfma_f32_16x16x32_bf16 v[4:7], v[168:171], v[218:221], v[4:7]
	v_mfma_f32_16x16x32_bf16 v[0:3], v[176:179], v[218:221], v[0:3]
	s_setprio 0
	s_add_i32 s52, s52, 2
	s_add_u32 s24, s24, 0x100
	s_addc_u32 s25, s25, 0
	s_add_u32 s50, s50, 0x100
	s_addc_u32 s51, s51, 0
	s_cmp_gt_u32 s52, 13
	s_barrier
	s_cbranch_scc0 .LBB0_722
	s_and_b64 vcc, exec, s[10:11]
	s_cbranch_vccz .LBB0_725
	s_barrier

.LBB0_861:
	s_add_u32 s20, s18, 0x100
	s_addc_u32 s21, s19, 0
	s_add_i32 s51, 0, 0x10000
	s_cmp_eq_u32 s50, 2
	s_cselect_b32 s25, s5, s21
	s_cselect_b32 s24, s4, s20
	v_add_u32_e32 v147, s51, v141
	s_cselect_b32 s23, s17, s49
	s_cselect_b32 s22, s16, s48
	s_add_i32 s52, 0, 0x14000
	ds_read_b128 v[148:151], v147
	ds_read_b128 v[152:155], v147 offset:1024
	ds_read_b128 v[156:159], v147 offset:2048
	ds_read_b128 v[160:163], v147 offset:3072
	v_add_u32_e32 v147, s52, v141
	ds_read_b128 v[164:167], v147
	ds_read_b128 v[168:171], v147 offset:1024
	ds_read_b128 v[172:175], v147 offset:2048
	ds_read_b128 v[176:179], v147 offset:3072
	v_lshl_add_u64 v[192:193], s[18:19], 0, v[136:137]
	s_add_i32 m0, s35, 0xc000
	ds_read_b128 v[180:183], v146
	ds_read_b128 v[184:187], v146 offset:1024
	ds_read_b128 v[188:191], v146 offset:2048
	ds_read_b128 v[202:205], v146 offset:3072
	ds_read_b128 v[206:209], v146 offset:4096
	ds_read_b128 v[210:213], v146 offset:5120
	ds_read_b128 v[214:217], v146 offset:6144
	ds_read_b128 v[218:221], v146 offset:7168
	global_load_lds_dwordx4 v[192:193], off
	v_lshl_add_u64 v[192:193], s[18:19], 0, v[138:139]
	s_add_i32 m0, s35, 0xe000
	s_nop 0
	global_load_lds_dwordx4 v[192:193], off
	s_waitcnt vmcnt(8)
	s_waitcnt lgkmcnt(0)
	s_barrier
	s_setprio 1
	s_waitcnt lgkmcnt(0)
	v_mfma_f32_16x16x32_bf16 v[126:129], v[148:151], v[180:183], v[126:129]
	v_mfma_f32_16x16x32_bf16 v[122:125], v[156:159], v[180:183], v[122:125]
	v_mfma_f32_16x16x32_bf16 v[114:117], v[148:151], v[188:191], v[114:117]
	v_mfma_f32_16x16x32_bf16 v[106:109], v[156:159], v[188:191], v[106:109]
	v_mfma_f32_16x16x32_bf16 v[98:101], v[148:151], v[206:209], v[98:101]
	v_mfma_f32_16x16x32_bf16 v[88:91], v[156:159], v[206:209], v[88:91]
	v_mfma_f32_16x16x32_bf16 v[80:83], v[148:151], v[214:217], v[80:83]
	v_mfma_f32_16x16x32_bf16 v[72:75], v[156:159], v[214:217], v[72:75]
	v_mfma_f32_16x16x32_bf16 v[126:129], v[152:155], v[184:187], v[126:129]
	v_mfma_f32_16x16x32_bf16 v[122:125], v[160:163], v[184:187], v[122:125]
	v_mfma_f32_16x16x32_bf16 v[114:117], v[152:155], v[202:205], v[114:117]
	v_mfma_f32_16x16x32_bf16 v[106:109], v[160:163], v[202:205], v[106:109]
	v_mfma_f32_16x16x32_bf16 v[98:101], v[152:155], v[210:213], v[98:101]
	v_mfma_f32_16x16x32_bf16 v[88:91], v[160:163], v[210:213], v[88:91]
	v_mfma_f32_16x16x32_bf16 v[80:83], v[152:155], v[218:221], v[80:83]
	v_mfma_f32_16x16x32_bf16 v[72:75], v[160:163], v[218:221], v[72:75]
	s_setprio 0
	s_setprio 1
	v_mfma_f32_16x16x32_bf16 v[118:121], v[164:167], v[180:183], v[118:121]
	v_mfma_f32_16x16x32_bf16 v[110:113], v[172:175], v[180:183], v[110:113]
	v_mfma_f32_16x16x32_bf16 v[102:105], v[164:167], v[188:191], v[102:105]
	v_mfma_f32_16x16x32_bf16 v[92:95], v[172:175], v[188:191], v[92:95]
	v_mfma_f32_16x16x32_bf16 v[84:87], v[164:167], v[206:209], v[84:87]
	v_mfma_f32_16x16x32_bf16 v[76:79], v[172:175], v[206:209], v[76:79]
	v_mfma_f32_16x16x32_bf16 v[68:71], v[164:167], v[214:217], v[68:71]
	v_mfma_f32_16x16x32_bf16 v[64:67], v[172:175], v[214:217], v[64:67]
	v_mfma_f32_16x16x32_bf16 v[118:121], v[168:171], v[184:187], v[118:121]
	v_mfma_f32_16x16x32_bf16 v[110:113], v[176:179], v[184:187], v[110:113]
	v_mfma_f32_16x16x32_bf16 v[102:105], v[168:171], v[202:205], v[102:105]
	v_mfma_f32_16x16x32_bf16 v[92:95], v[176:179], v[202:205], v[92:95]
	v_mfma_f32_16x16x32_bf16 v[84:87], v[168:171], v[210:213], v[84:87]
	v_mfma_f32_16x16x32_bf16 v[76:79], v[176:179], v[210:213], v[76:79]
	v_mfma_f32_16x16x32_bf16 v[68:71], v[168:171], v[218:221], v[68:71]
	v_mfma_f32_16x16x32_bf16 v[64:67], v[176:179], v[218:221], v[64:67]
	s_setprio 0
	s_barrier
	s_add_i32 s18, s51, s34
	v_lshl_add_u64 v[192:193], s[22:23], 0, v[96:97]
	s_mov_b32 m0, s18
	ds_read_b128 v[180:183], v146 offset:16384
	ds_read_b128 v[184:187], v146 offset:17408
	ds_read_b128 v[188:191], v146 offset:18432
	ds_read_b128 v[202:205], v146 offset:19456
	ds_read_b128 v[206:209], v146 offset:20480
	ds_read_b128 v[210:213], v146 offset:21504
	ds_read_b128 v[214:217], v146 offset:22528
	ds_read_b128 v[218:221], v146 offset:23552
	global_load_lds_dwordx4 v[192:193], off
	s_add_i32 m0, s18, 0x2000
	s_add_u32 s18, s22, 0x18000
	v_lshl_add_u64 v[194:195], s[22:23], 0, v[130:131]
	s_addc_u32 s19, s23, 0
	s_add_i32 s51, s52, s34
	global_load_lds_dwordx4 v[194:195], off
	v_lshl_add_u64 v[196:197], s[18:19], 0, v[96:97]
	s_mov_b32 m0, s51
	v_lshl_add_u64 v[198:199], s[24:25], 0, v[132:133]
	global_load_lds_dwordx4 v[196:197], off
	v_lshl_add_u64 v[196:197], s[18:19], 0, v[130:131]
	s_add_i32 m0, s51, 0x2000
	s_nop 0
	global_load_lds_dwordx4 v[196:197], off
	v_lshl_add_u64 v[196:197], s[24:25], 0, v[134:135]
	s_mov_b32 m0, s35
	s_nop 0
	global_load_lds_dwordx4 v[196:197], off
	s_mov_b32 m0, s36
	s_nop 0
	global_load_lds_dwordx4 v[198:199], off
	s_waitcnt vmcnt(8)
	s_waitcnt lgkmcnt(0)
	s_barrier
	s_setprio 1
	s_waitcnt lgkmcnt(0)
	v_mfma_f32_16x16x32_bf16 v[60:63], v[148:151], v[180:183], v[60:63]
	v_mfma_f32_16x16x32_bf16 v[56:59], v[156:159], v[180:183], v[56:59]
	v_mfma_f32_16x16x32_bf16 v[48:51], v[148:151], v[188:191], v[48:51]
	v_mfma_f32_16x16x32_bf16 v[40:43], v[156:159], v[188:191], v[40:43]
	v_mfma_f32_16x16x32_bf16 v[32:35], v[148:151], v[206:209], v[32:35]
	v_mfma_f32_16x16x32_bf16 v[24:27], v[156:159], v[206:209], v[24:27]
	v_mfma_f32_16x16x32_bf16 v[16:19], v[148:151], v[214:217], v[16:19]
	v_mfma_f32_16x16x32_bf16 v[8:11], v[156:159], v[214:217], v[8:11]
	v_mfma_f32_16x16x32_bf16 v[60:63], v[152:155], v[184:187], v[60:63]
	v_mfma_f32_16x16x32_bf16 v[56:59], v[160:163], v[184:187], v[56:59]
	v_mfma_f32_16x16x32_bf16 v[48:51], v[152:155], v[202:205], v[48:51]
	v_mfma_f32_16x16x32_bf16 v[40:43], v[160:163], v[202:205], v[40:43]
	v_mfma_f32_16x16x32_bf16 v[32:35], v[152:155], v[210:213], v[32:35]
	v_mfma_f32_16x16x32_bf16 v[24:27], v[160:163], v[210:213], v[24:27]
	v_mfma_f32_16x16x32_bf16 v[16:19], v[152:155], v[218:221], v[16:19]
	v_mfma_f32_16x16x32_bf16 v[8:11], v[160:163], v[218:221], v[8:11]
	s_setprio 0
	s_setprio 1
	v_mfma_f32_16x16x32_bf16 v[52:55], v[164:167], v[180:183], v[52:55]
	v_mfma_f32_16x16x32_bf16 v[44:47], v[172:175], v[180:183], v[44:47]
	v_mfma_f32_16x16x32_bf16 v[36:39], v[164:167], v[188:191], v[36:39]
	v_mfma_f32_16x16x32_bf16 v[28:31], v[172:175], v[188:191], v[28:31]
	v_mfma_f32_16x16x32_bf16 v[20:23], v[164:167], v[206:209], v[20:23]
	v_mfma_f32_16x16x32_bf16 v[12:15], v[172:175], v[206:209], v[12:15]
	v_mfma_f32_16x16x32_bf16 v[4:7], v[164:167], v[214:217], v[4:7]
	v_mfma_f32_16x16x32_bf16 v[0:3], v[172:175], v[214:217], v[0:3]
	v_mfma_f32_16x16x32_bf16 v[52:55], v[168:171], v[184:187], v[52:55]
	v_mfma_f32_16x16x32_bf16 v[44:47], v[176:179], v[184:187], v[44:47]
	v_mfma_f32_16x16x32_bf16 v[36:39], v[168:171], v[202:205], v[36:39]
	v_mfma_f32_16x16x32_bf16 v[28:31], v[176:179], v[202:205], v[28:31]
	v_mfma_f32_16x16x32_bf16 v[20:23], v[168:171], v[210:213], v[20:23]
	v_mfma_f32_16x16x32_bf16 v[12:15], v[176:179], v[210:213], v[12:15]
	v_mfma_f32_16x16x32_bf16 v[4:7], v[168:171], v[218:221], v[4:7]
	v_mfma_f32_16x16x32_bf16 v[0:3], v[176:179], v[218:221], v[0:3]
	s_setprio 0
	s_barrier
	s_add_i32 s51, 0, 0x18000
	v_add_u32_e32 v147, s51, v141
	s_add_i32 s52, 0, 0x1c000
	ds_read_b128 v[148:151], v147
	ds_read_b128 v[152:155], v147 offset:1024
	ds_read_b128 v[156:159], v147 offset:2048
	ds_read_b128 v[160:163], v147 offset:3072
	v_add_u32_e32 v147, s52, v141
	ds_read_b128 v[164:167], v147
	ds_read_b128 v[168:171], v147 offset:1024
	ds_read_b128 v[172:175], v147 offset:2048
	ds_read_b128 v[176:179], v147 offset:3072
	s_add_u32 s18, s24, 0x50000
	s_addc_u32 s19, s25, 0
	s_mov_b32 m0, s37
	v_lshl_add_u64 v[200:201], s[18:19], 0, v[134:135]
	ds_read_b128 v[180:183], v146 offset:32768
	ds_read_b128 v[184:187], v146 offset:33792
	ds_read_b128 v[188:191], v146 offset:34816
	ds_read_b128 v[202:205], v146 offset:35840
	ds_read_b128 v[206:209], v146 offset:36864
	ds_read_b128 v[210:213], v146 offset:37888
	ds_read_b128 v[214:217], v146 offset:38912
	ds_read_b128 v[218:221], v146 offset:39936
	global_load_lds_dwordx4 v[200:201], off
	v_lshl_add_u64 v[200:201], s[18:19], 0, v[132:133]
	s_mov_b32 m0, s38
	s_nop 0
	global_load_lds_dwordx4 v[200:201], off
	s_waitcnt vmcnt(8)
	s_waitcnt lgkmcnt(0)
	s_barrier
	s_setprio 1
	s_waitcnt lgkmcnt(0)
	v_mfma_f32_16x16x32_bf16 v[126:129], v[148:151], v[180:183], v[126:129]
	v_mfma_f32_16x16x32_bf16 v[122:125], v[156:159], v[180:183], v[122:125]
	v_mfma_f32_16x16x32_bf16 v[114:117], v[148:151], v[188:191], v[114:117]
	v_mfma_f32_16x16x32_bf16 v[106:109], v[156:159], v[188:191], v[106:109]
	v_mfma_f32_16x16x32_bf16 v[98:101], v[148:151], v[206:209], v[98:101]
	v_mfma_f32_16x16x32_bf16 v[88:91], v[156:159], v[206:209], v[88:91]
	v_mfma_f32_16x16x32_bf16 v[80:83], v[148:151], v[214:217], v[80:83]
	v_mfma_f32_16x16x32_bf16 v[72:75], v[156:159], v[214:217], v[72:75]
	v_mfma_f32_16x16x32_bf16 v[126:129], v[152:155], v[184:187], v[126:129]
	v_mfma_f32_16x16x32_bf16 v[122:125], v[160:163], v[184:187], v[122:125]
	v_mfma_f32_16x16x32_bf16 v[114:117], v[152:155], v[202:205], v[114:117]
	v_mfma_f32_16x16x32_bf16 v[106:109], v[160:163], v[202:205], v[106:109]
	v_mfma_f32_16x16x32_bf16 v[98:101], v[152:155], v[210:213], v[98:101]
	v_mfma_f32_16x16x32_bf16 v[88:91], v[160:163], v[210:213], v[88:91]
	v_mfma_f32_16x16x32_bf16 v[80:83], v[152:155], v[218:221], v[80:83]
	v_mfma_f32_16x16x32_bf16 v[72:75], v[160:163], v[218:221], v[72:75]
	s_setprio 0
	s_setprio 1
	v_mfma_f32_16x16x32_bf16 v[118:121], v[164:167], v[180:183], v[118:121]
	v_mfma_f32_16x16x32_bf16 v[110:113], v[172:175], v[180:183], v[110:113]
	v_mfma_f32_16x16x32_bf16 v[102:105], v[164:167], v[188:191], v[102:105]
	v_mfma_f32_16x16x32_bf16 v[92:95], v[172:175], v[188:191], v[92:95]
	v_mfma_f32_16x16x32_bf16 v[84:87], v[164:167], v[206:209], v[84:87]
	v_mfma_f32_16x16x32_bf16 v[76:79], v[172:175], v[206:209], v[76:79]
	v_mfma_f32_16x16x32_bf16 v[68:71], v[164:167], v[214:217], v[68:71]
	v_mfma_f32_16x16x32_bf16 v[64:67], v[172:175], v[214:217], v[64:67]
	v_mfma_f32_16x16x32_bf16 v[118:121], v[168:171], v[184:187], v[118:121]
	v_mfma_f32_16x16x32_bf16 v[110:113], v[176:179], v[184:187], v[110:113]
	v_mfma_f32_16x16x32_bf16 v[102:105], v[168:171], v[202:205], v[102:105]
	v_mfma_f32_16x16x32_bf16 v[92:95], v[176:179], v[202:205], v[92:95]
	v_mfma_f32_16x16x32_bf16 v[84:87], v[168:171], v[210:213], v[84:87]
	v_mfma_f32_16x16x32_bf16 v[76:79], v[176:179], v[210:213], v[76:79]
	v_mfma_f32_16x16x32_bf16 v[68:71], v[168:171], v[218:221], v[68:71]
	v_mfma_f32_16x16x32_bf16 v[64:67], v[176:179], v[218:221], v[64:67]
	s_setprio 0
	s_barrier
	s_add_i32 s18, s51, s34
	v_lshl_add_u64 v[192:193], v[192:193], 0, s[64:65]
	s_mov_b32 m0, s18
	ds_read_b128 v[180:183], v146 offset:49152
	ds_read_b128 v[184:187], v146 offset:50176
	ds_read_b128 v[188:191], v146 offset:51200
	ds_read_b128 v[202:205], v146 offset:52224
	ds_read_b128 v[206:209], v146 offset:53248
	ds_read_b128 v[210:213], v146 offset:54272
	ds_read_b128 v[214:217], v146 offset:55296
	ds_read_b128 v[218:221], v146 offset:56320
	global_load_lds_dwordx4 v[192:193], off
	s_add_i32 m0, s18, 0x2000
	s_add_u32 s18, s22, 0x18080
	v_lshl_add_u64 v[192:193], v[194:195], 0, s[64:65]
	s_addc_u32 s19, s23, 0
	s_add_i32 s22, s52, s34
	global_load_lds_dwordx4 v[192:193], off
	v_lshl_add_u64 v[192:193], s[18:19], 0, v[96:97]
	s_mov_b32 m0, s22
	s_nop 0
	global_load_lds_dwordx4 v[192:193], off
	v_lshl_add_u64 v[192:193], s[18:19], 0, v[130:131]
	s_add_i32 m0, s22, 0x2000
	s_nop 0
	global_load_lds_dwordx4 v[192:193], off
	v_lshl_add_u64 v[192:193], v[196:197], 0, s[64:65]
	s_mov_b32 m0, s39
	s_nop 0
	global_load_lds_dwordx4 v[192:193], off
	v_lshl_add_u64 v[192:193], v[198:199], 0, s[64:65]
	s_mov_b32 m0, s40
	s_nop 0
	global_load_lds_dwordx4 v[192:193], off
	s_waitcnt vmcnt(8)
	s_waitcnt lgkmcnt(0)
	s_barrier
	s_setprio 1
	s_waitcnt lgkmcnt(0)
	v_mfma_f32_16x16x32_bf16 v[60:63], v[148:151], v[180:183], v[60:63]
	v_mfma_f32_16x16x32_bf16 v[56:59], v[156:159], v[180:183], v[56:59]
	v_mfma_f32_16x16x32_bf16 v[48:51], v[148:151], v[188:191], v[48:51]
	v_mfma_f32_16x16x32_bf16 v[40:43], v[156:159], v[188:191], v[40:43]
	v_mfma_f32_16x16x32_bf16 v[32:35], v[148:151], v[206:209], v[32:35]
	v_mfma_f32_16x16x32_bf16 v[24:27], v[156:159], v[206:209], v[24:27]
	v_mfma_f32_16x16x32_bf16 v[16:19], v[148:151], v[214:217], v[16:19]
	v_mfma_f32_16x16x32_bf16 v[8:11], v[156:159], v[214:217], v[8:11]
	v_mfma_f32_16x16x32_bf16 v[60:63], v[152:155], v[184:187], v[60:63]
	v_mfma_f32_16x16x32_bf16 v[56:59], v[160:163], v[184:187], v[56:59]
	v_mfma_f32_16x16x32_bf16 v[48:51], v[152:155], v[202:205], v[48:51]
	v_mfma_f32_16x16x32_bf16 v[40:43], v[160:163], v[202:205], v[40:43]
	v_mfma_f32_16x16x32_bf16 v[32:35], v[152:155], v[210:213], v[32:35]
	v_mfma_f32_16x16x32_bf16 v[24:27], v[160:163], v[210:213], v[24:27]
	v_mfma_f32_16x16x32_bf16 v[16:19], v[152:155], v[218:221], v[16:19]
	v_mfma_f32_16x16x32_bf16 v[8:11], v[160:163], v[218:221], v[8:11]
	s_setprio 0
	s_setprio 1
	v_mfma_f32_16x16x32_bf16 v[52:55], v[164:167], v[180:183], v[52:55]
	v_mfma_f32_16x16x32_bf16 v[44:47], v[172:175], v[180:183], v[44:47]
	v_mfma_f32_16x16x32_bf16 v[36:39], v[164:167], v[188:191], v[36:39]
	v_mfma_f32_16x16x32_bf16 v[28:31], v[172:175], v[188:191], v[28:31]
	v_mfma_f32_16x16x32_bf16 v[20:23], v[164:167], v[206:209], v[20:23]
	v_mfma_f32_16x16x32_bf16 v[12:15], v[172:175], v[206:209], v[12:15]
	v_mfma_f32_16x16x32_bf16 v[4:7], v[164:167], v[214:217], v[4:7]
	v_mfma_f32_16x16x32_bf16 v[0:3], v[172:175], v[214:217], v[0:3]
	v_mfma_f32_16x16x32_bf16 v[52:55], v[168:171], v[184:187], v[52:55]
	v_mfma_f32_16x16x32_bf16 v[44:47], v[176:179], v[184:187], v[44:47]
	v_mfma_f32_16x16x32_bf16 v[36:39], v[168:171], v[202:205], v[36:39]
	v_mfma_f32_16x16x32_bf16 v[28:31], v[176:179], v[202:205], v[28:31]
	v_mfma_f32_16x16x32_bf16 v[20:23], v[168:171], v[210:213], v[20:23]
	v_mfma_f32_16x16x32_bf16 v[12:15], v[176:179], v[210:213], v[12:15]
	v_mfma_f32_16x16x32_bf16 v[4:7], v[168:171], v[218:221], v[4:7]
	v_mfma_f32_16x16x32_bf16 v[0:3], v[176:179], v[218:221], v[0:3]
	s_setprio 0
	s_add_i32 s50, s50, 2
	s_add_u32 s48, s48, 0x100
	s_addc_u32 s49, s49, 0
	s_cmp_gt_u32 s50, 3
	s_mov_b64 s[18:19], s[20:21]
	s_barrier
	s_cbranch_scc0 .LBB0_861
	s_and_b64 vcc, exec, s[12:13]
	s_cbranch_vccz .LBB0_864
	s_barrier

.Lat7A_A_h1:
	s_or_b64 exec, exec, s[4:5]
	global_load_dwordx4 v[132:135], v[200:201], off offset:384

	s_sub_u32 s98, s98, 0x3000
	s_subb_u32 s99, s99, 0

	s_waitcnt lgkmcnt(7)
	v_mfma_f32_32x32x16_bf16 v[32:47], v[176:179], v[108:111], v[32:47]
	v_exp_f32_e32 v80, v80
	v_exp_f32_e32 v81, v81
	v_exp_f32_e32 v82, v82
	v_add_f32_e32 v251, v80, v81
	v_cvt_pk_bf16_f32 v64, v64, v65
	v_exp_f32_e32 v83, v83
	v_mfma_f32_32x32x16_bf16 v[48:63], v[140:143], v[112:115], v[48:63]
	v_add_f32_e32 v251, v82, v251
	v_exp_f32_e32 v84, v84
	v_add_f32_e32 v251, v83, v251
	v_cvt_pk_bf16_f32 v65, v66, v67
	v_exp_f32_e32 v85, v85
	v_add_f32_e32 v251, v84, v251
	s_waitcnt lgkmcnt(6)
	v_mfma_f32_32x32x16_bf16 v[32:47], v[160:163], v[112:115], v[32:47]
	v_exp_f32_e32 v86, v86
	v_add_f32_e32 v251, v85, v251
	v_cvt_pk_bf16_f32 v66, v68, v69
	v_exp_f32_e32 v87, v87
	v_add_f32_e32 v251, v86, v251
	v_exp_f32_e32 v88, v88
	v_add_f32_e32 v251, v87, v251
	s_waitcnt lgkmcnt(5)
	v_mfma_f32_32x32x16_bf16 v[48:63], v[148:151], v[116:119], v[48:63]
	v_cvt_pk_bf16_f32 v67, v70, v71
	v_exp_f32_e32 v89, v89
	v_add_f32_e32 v251, v88, v251
	v_exp_f32_e32 v90, v90
	v_add_f32_e32 v251, v89, v251
	v_cvt_pk_bf16_f32 v68, v72, v73
	v_exp_f32_e32 v91, v91
	v_add_u32_e32 v198, v207, v184
	ds_read_b128 v[210:213], v198 offset:53760
	ds_read_b128 v[214:217], v198 offset:49152
	ds_read_b128 v[218:221], v198 offset:49184
	ds_read_b128 v[222:225], v198 offset:53792
	ds_read_b128 v[226:229], v198 offset:49216
	ds_read_b128 v[230:233], v198 offset:53824
	ds_read_b128 v[234:237], v198 offset:49248
	ds_read_b128 v[238:241], v198 offset:53856
	s_waitcnt lgkmcnt(11)
	v_mfma_f32_32x32x16_bf16 v[32:47], v[168:171], v[116:119], v[32:47]
	v_add_f32_e32 v251, v90, v251
	v_exp_f32_e32 v92, v92
	v_add_f32_e32 v251, v91, v251
	v_cvt_pk_bf16_f32 v69, v74, v75
	v_exp_f32_e32 v93, v93
	v_add_f32_e32 v251, v92, v251
	v_mfma_f32_32x32x16_bf16 v[48:63], v[136:139], v[120:123], v[48:63]
	v_exp_f32_e32 v94, v94
	v_add_f32_e32 v251, v93, v251
	v_cvt_pk_bf16_f32 v70, v76, v77
	v_exp_f32_e32 v95, v95
	v_add_f32_e32 v251, v94, v251
	v_add_f32_e32 v251, v95, v251
	v_cvt_pk_bf16_f32 v71, v78, v79
	v_cvt_pk_bf16_f32 v80, v80, v81
	s_waitcnt lgkmcnt(10)
	v_mfma_f32_32x32x16_bf16 v[32:47], v[144:147], v[120:123], v[32:47]
	v_cvt_pk_bf16_f32 v81, v82, v83
	v_cvt_pk_bf16_f32 v82, v84, v85
	v_cvt_pk_bf16_f32 v83, v86, v87
	v_cvt_pk_bf16_f32 v84, v88, v89
	v_cvt_pk_bf16_f32 v85, v90, v91
	v_cvt_pk_bf16_f32 v86, v92, v93
	v_cvt_pk_bf16_f32 v87, v94, v95
	v_add_f32_e32 v195, v195, v251
	v_add_f32_e32 v199, v199, v195
	s_add_i32 s92, s79, 2
	s_waitcnt lgkmcnt(0)
	s_barrier

	v_add_u32_e32 v197, s6, v204
	s_setprio 1
	v_mfma_f32_32x32x16_bf16 v[0:15], v[64:67], v[210:213], v[0:15]
	ds_read_b128 v[172:175], v197
	ds_read_b128 v[152:155], v197 offset:32
	v_mfma_f32_32x32x16_bf16 v[0:15], v[68:71], v[222:225], v[0:15]
	ds_read_b128 v[180:183], v197 offset:6656
	ds_read_b128 v[164:167], v197 offset:6688
	v_mfma_f32_32x32x16_bf16 v[0:15], v[80:83], v[230:233], v[0:15]
	ds_read_b128 v[156:159], v197 offset:64
	ds_read_b128 v[140:143], v197 offset:96
	v_mfma_f32_32x32x16_bf16 v[0:15], v[84:87], v[238:241], v[0:15]
	s_setprio 0
	ds_read_b128 v[176:179], v197 offset:6720
	ds_read_b128 v[160:163], v197 offset:6752
	v_mfma_f32_32x32x16_bf16 v[16:31], v[64:67], v[214:217], v[16:31]
	ds_read_b128 v[148:151], v197 offset:128
	ds_read_b128 v[136:139], v197 offset:160
	v_mfma_f32_32x32x16_bf16 v[16:31], v[68:71], v[218:221], v[16:31]
	ds_read_b128 v[168:171], v197 offset:6784
	ds_read_b128 v[144:147], v197 offset:6816
	v_mfma_f32_32x32x16_bf16 v[16:31], v[80:83], v[226:229], v[16:31]
	s_add_i32 s4, s74, 1
	s_cmp_lg_u32 s74, 2
	s_cselect_b32 s91, s4, 0
	s_add_i32 s4, s93, 0x80
	v_lshl_add_u64 v[188:189], v[188:189], 0, s[82:83]
	v_lshl_add_u64 v[186:187], v[186:187], 0, s[82:83]
	v_lshl_add_u64 v[190:191], v[190:191], 0, s[66:67]
	v_lshl_add_u64 v[192:193], v[98:99], 0, s[66:67]

	v_mfma_f32_32x32x16_bf16 v[16:31], v[84:87], v[234:237], v[16:31]
	s_cmp_ge_u32 s92, s87
	s_cbranch_scc1 .LBB0_1049
	v_mov_b64_e32 v[98:99], v[192:193]
	s_mov_b32 s93, s4
	s_mov_b32 s79, s92
	s_branch .LBB0_1039


.Lat7B_A_h1:
	s_or_b64 exec, exec, s[4:5]
	global_load_dwordx4 v[132:135], v[200:201], off offset:384

	s_sub_u32 s98, s98, 0x3000
	s_subb_u32 s99, s99, 0

	s_waitcnt lgkmcnt(7)
	v_mfma_f32_32x32x16_bf16 v[32:47], v[176:179], v[108:111], v[32:47]
	v_exp_f32_e32 v80, v80
	v_exp_f32_e32 v81, v81
	v_exp_f32_e32 v82, v82
	v_add_f32_e32 v251, v80, v81
	v_cvt_pk_bf16_f32 v64, v64, v65
	v_exp_f32_e32 v83, v83
	v_mfma_f32_32x32x16_bf16 v[48:63], v[140:143], v[112:115], v[48:63]
	v_add_f32_e32 v251, v82, v251
	v_exp_f32_e32 v84, v84
	v_add_f32_e32 v251, v83, v251
	v_cvt_pk_bf16_f32 v65, v66, v67
	v_exp_f32_e32 v85, v85
	v_add_f32_e32 v251, v84, v251
	s_waitcnt lgkmcnt(6)
	v_mfma_f32_32x32x16_bf16 v[32:47], v[160:163], v[112:115], v[32:47]
	v_exp_f32_e32 v86, v86
	v_add_f32_e32 v251, v85, v251
	v_cvt_pk_bf16_f32 v66, v68, v69
	v_exp_f32_e32 v87, v87
	v_add_f32_e32 v251, v86, v251
	v_exp_f32_e32 v88, v88
	v_add_f32_e32 v251, v87, v251
	s_waitcnt lgkmcnt(5)
	v_mfma_f32_32x32x16_bf16 v[48:63], v[148:151], v[116:119], v[48:63]
	v_cvt_pk_bf16_f32 v67, v70, v71
	v_exp_f32_e32 v89, v89
	v_add_f32_e32 v251, v88, v251
	v_exp_f32_e32 v90, v90
	v_add_f32_e32 v251, v89, v251
	v_cvt_pk_bf16_f32 v68, v72, v73
	v_exp_f32_e32 v91, v91
	v_add_u32_e32 v196, v208, v184
	ds_read_b128 v[212:215], v196 offset:53760
	ds_read_b128 v[216:219], v196 offset:49152
	ds_read_b128 v[220:223], v196 offset:49184
	ds_read_b128 v[224:227], v196 offset:53792
	ds_read_b128 v[228:231], v196 offset:49216
	ds_read_b128 v[232:235], v196 offset:53824
	ds_read_b128 v[236:239], v196 offset:49248
	ds_read_b128 v[240:243], v196 offset:53856
	s_waitcnt lgkmcnt(11)
	v_mfma_f32_32x32x16_bf16 v[32:47], v[168:171], v[116:119], v[32:47]
	v_add_f32_e32 v251, v90, v251
	v_exp_f32_e32 v92, v92
	v_add_f32_e32 v251, v91, v251
	v_cvt_pk_bf16_f32 v69, v74, v75
	v_exp_f32_e32 v93, v93
	v_add_f32_e32 v251, v92, v251
	v_mfma_f32_32x32x16_bf16 v[48:63], v[136:139], v[120:123], v[48:63]
	v_exp_f32_e32 v94, v94
	v_add_f32_e32 v251, v93, v251
	v_cvt_pk_bf16_f32 v70, v76, v77
	v_exp_f32_e32 v95, v95
	v_add_f32_e32 v251, v94, v251
	v_add_f32_e32 v251, v95, v251
	v_cvt_pk_bf16_f32 v71, v78, v79
	v_cvt_pk_bf16_f32 v80, v80, v81
	s_waitcnt lgkmcnt(10)
	v_mfma_f32_32x32x16_bf16 v[32:47], v[144:147], v[120:123], v[32:47]
	v_cvt_pk_bf16_f32 v81, v82, v83
	v_cvt_pk_bf16_f32 v82, v84, v85
	v_cvt_pk_bf16_f32 v83, v86, v87
	v_cvt_pk_bf16_f32 v84, v88, v89
	v_cvt_pk_bf16_f32 v85, v90, v91
	v_cvt_pk_bf16_f32 v86, v92, v93
	v_cvt_pk_bf16_f32 v87, v94, v95
	v_add_f32_e32 v195, v195, v251
	v_add_f32_e32 v198, v198, v195
	s_add_i32 s40, s40, 2
	s_waitcnt lgkmcnt(0)
	s_barrier

	v_add_u32_e32 v197, s6, v209
	s_setprio 1
	v_mfma_f32_32x32x16_bf16 v[0:15], v[64:67], v[212:215], v[0:15]
	ds_read_b128 v[172:175], v197
	ds_read_b128 v[152:155], v197 offset:32
	v_mfma_f32_32x32x16_bf16 v[0:15], v[68:71], v[224:227], v[0:15]
	ds_read_b128 v[180:183], v197 offset:6656
	ds_read_b128 v[164:167], v197 offset:6688
	v_mfma_f32_32x32x16_bf16 v[0:15], v[80:83], v[232:235], v[0:15]
	ds_read_b128 v[156:159], v197 offset:64
	ds_read_b128 v[140:143], v197 offset:96
	v_mfma_f32_32x32x16_bf16 v[0:15], v[84:87], v[240:243], v[0:15]
	s_setprio 0
	ds_read_b128 v[176:179], v197 offset:6720
	ds_read_b128 v[160:163], v197 offset:6752
	v_mfma_f32_32x32x16_bf16 v[16:31], v[64:67], v[216:219], v[16:31]
	ds_read_b128 v[148:151], v197 offset:128
	ds_read_b128 v[136:139], v197 offset:160
	v_mfma_f32_32x32x16_bf16 v[16:31], v[68:71], v[220:223], v[16:31]
	ds_read_b128 v[168:171], v197 offset:6784
	ds_read_b128 v[144:147], v197 offset:6816
	v_mfma_f32_32x32x16_bf16 v[16:31], v[80:83], v[228:231], v[16:31]
	s_add_i32 s4, s68, 1
	s_cmp_lg_u32 s68, 2
	s_cselect_b32 s90, s4, 0
	v_lshl_add_u64 v[98:99], v[98:99], 0, s[82:83]
	v_lshl_add_u64 v[202:203], v[202:203], 0, s[82:83]
	v_lshl_add_u64 v[204:205], v[204:205], 0, s[66:67]

	v_mfma_f32_32x32x16_bf16 v[16:31], v[84:87], v[236:239], v[16:31]
	s_cmp_ge_u32 s40, s69
	s_cbranch_scc0 .LBB0_1106
	s_branch .LBB0_1115


.LBB0_1237:
	s_add_u32 s28, s26, 0xfffc0080
	s_addc_u32 s29, s27, -1
	s_add_i32 s52, 0, 0x10000
	s_cmp_eq_u32 s51, 12
	s_cselect_b32 s31, s17, s29
	s_cselect_b32 s30, s23, s28
	s_cselect_b32 s29, s15, s50
	s_cselect_b32 s28, s25, s49
	s_add_i32 s54, 0, 0x14000
	v_add_u32_e32 v134, s52, v245
	v_add_u32_e32 v150, s54, v245
	ds_read_b128 v[122:125], v134
	ds_read_b128 v[126:129], v134 offset:1024
	ds_read_b128 v[130:133], v134 offset:2048
	ds_read_b128 v[134:137], v134 offset:3072
	ds_read_b128 v[138:141], v150
	ds_read_b128 v[142:145], v150 offset:1024
	ds_read_b128 v[146:149], v150 offset:2048
	ds_read_b128 v[150:153], v150 offset:3072
	v_lshl_add_u64 v[194:195], s[26:27], 0, v[204:205]
	s_add_i32 m0, s40, 0xc000
	ds_read_b128 v[162:165], v199
	ds_read_b128 v[166:169], v199 offset:1024
	ds_read_b128 v[170:173], v199 offset:2048
	ds_read_b128 v[174:177], v199 offset:3072
	ds_read_b128 v[178:181], v199 offset:4096
	ds_read_b128 v[182:185], v199 offset:5120
	ds_read_b128 v[186:189], v199 offset:6144
	ds_read_b128 v[208:211], v199 offset:7168
	global_load_lds_dwordx4 v[194:195], off
	v_lshl_add_u64 v[194:195], s[26:27], 0, v[206:207]
	s_add_i32 m0, s40, 0xe000
	s_nop 0
	global_load_lds_dwordx4 v[194:195], off
	s_waitcnt vmcnt(8)
	s_waitcnt lgkmcnt(0)
	s_barrier
	s_setprio 1
	s_waitcnt lgkmcnt(0)
	v_mfma_f32_16x16x32_bf16 v[158:161], v[122:125], v[162:165], v[158:161]
	v_mfma_f32_16x16x32_bf16 v[154:157], v[130:133], v[162:165], v[154:157]
	v_mfma_f32_16x16x32_bf16 v[110:113], v[122:125], v[170:173], v[110:113]
	v_mfma_f32_16x16x32_bf16 v[106:109], v[130:133], v[170:173], v[106:109]
	v_mfma_f32_16x16x32_bf16 v[92:95], v[122:125], v[178:181], v[92:95]
	v_mfma_f32_16x16x32_bf16 v[88:91], v[130:133], v[178:181], v[88:91]
	v_mfma_f32_16x16x32_bf16 v[76:79], v[122:125], v[186:189], v[76:79]
	v_mfma_f32_16x16x32_bf16 v[72:75], v[130:133], v[186:189], v[72:75]
	v_mfma_f32_16x16x32_bf16 v[158:161], v[126:129], v[166:169], v[158:161]
	v_mfma_f32_16x16x32_bf16 v[154:157], v[134:137], v[166:169], v[154:157]
	v_mfma_f32_16x16x32_bf16 v[110:113], v[126:129], v[174:177], v[110:113]
	v_mfma_f32_16x16x32_bf16 v[106:109], v[134:137], v[174:177], v[106:109]
	v_mfma_f32_16x16x32_bf16 v[92:95], v[126:129], v[182:185], v[92:95]
	v_mfma_f32_16x16x32_bf16 v[88:91], v[134:137], v[182:185], v[88:91]
	v_mfma_f32_16x16x32_bf16 v[76:79], v[126:129], v[208:211], v[76:79]
	v_mfma_f32_16x16x32_bf16 v[72:75], v[134:137], v[208:211], v[72:75]
	s_setprio 0
	s_setprio 1
	v_mfma_f32_16x16x32_bf16 v[118:121], v[138:141], v[162:165], v[118:121]
	v_mfma_f32_16x16x32_bf16 v[114:117], v[146:149], v[162:165], v[114:117]
	v_mfma_f32_16x16x32_bf16 v[102:105], v[138:141], v[170:173], v[102:105]
	v_mfma_f32_16x16x32_bf16 v[98:101], v[146:149], v[170:173], v[98:101]
	v_mfma_f32_16x16x32_bf16 v[84:87], v[138:141], v[178:181], v[84:87]
	v_mfma_f32_16x16x32_bf16 v[80:83], v[146:149], v[178:181], v[80:83]
	v_mfma_f32_16x16x32_bf16 v[68:71], v[138:141], v[186:189], v[68:71]
	v_mfma_f32_16x16x32_bf16 v[64:67], v[146:149], v[186:189], v[64:67]
	v_mfma_f32_16x16x32_bf16 v[118:121], v[142:145], v[166:169], v[118:121]
	v_mfma_f32_16x16x32_bf16 v[114:117], v[150:153], v[166:169], v[114:117]
	v_mfma_f32_16x16x32_bf16 v[102:105], v[142:145], v[174:177], v[102:105]
	v_mfma_f32_16x16x32_bf16 v[98:101], v[150:153], v[174:177], v[98:101]
	v_mfma_f32_16x16x32_bf16 v[84:87], v[142:145], v[182:185], v[84:87]
	v_mfma_f32_16x16x32_bf16 v[80:83], v[150:153], v[182:185], v[80:83]
	v_mfma_f32_16x16x32_bf16 v[68:71], v[142:145], v[208:211], v[68:71]
	v_mfma_f32_16x16x32_bf16 v[64:67], v[150:153], v[208:211], v[64:67]
	s_setprio 0
	s_barrier
	s_add_i32 s52, s52, s39
	v_lshl_add_u64 v[194:195], s[28:29], 0, v[96:97]
	s_mov_b32 m0, s52
	ds_read_b128 v[162:165], v199 offset:16384
	ds_read_b128 v[166:169], v199 offset:17408
	ds_read_b128 v[170:173], v199 offset:18432
	ds_read_b128 v[174:177], v199 offset:19456
	ds_read_b128 v[178:181], v199 offset:20480
	ds_read_b128 v[182:185], v199 offset:21504
	ds_read_b128 v[186:189], v199 offset:22528
	ds_read_b128 v[208:211], v199 offset:23552
	global_load_lds_dwordx4 v[194:195], off
	s_add_i32 m0, s52, 0x2000
	s_add_u32 s52, s28, 0x40000
	v_lshl_add_u64 v[196:197], s[28:29], 0, v[202:203]
	s_addc_u32 s53, s29, 0
	s_add_i32 s54, s54, s39
	global_load_lds_dwordx4 v[196:197], off
	v_lshl_add_u64 v[200:201], s[52:53], 0, v[96:97]
	s_mov_b32 m0, s54
	v_lshl_add_u64 v[212:213], s[30:31], 0, v[192:193]
	global_load_lds_dwordx4 v[200:201], off
	v_lshl_add_u64 v[200:201], s[52:53], 0, v[202:203]
	s_add_i32 m0, s54, 0x2000
	s_nop 0
	global_load_lds_dwordx4 v[200:201], off
	v_lshl_add_u64 v[200:201], s[30:31], 0, v[190:191]
	s_mov_b32 m0, s40
	s_nop 0
	global_load_lds_dwordx4 v[200:201], off
	s_mov_b32 m0, s41
	s_nop 0
	global_load_lds_dwordx4 v[212:213], off
	s_waitcnt vmcnt(8)
	s_waitcnt lgkmcnt(0)
	s_barrier
	s_setprio 1
	s_waitcnt lgkmcnt(0)
	v_mfma_f32_16x16x32_bf16 v[60:63], v[122:125], v[162:165], v[60:63]
	v_mfma_f32_16x16x32_bf16 v[56:59], v[130:133], v[162:165], v[56:59]
	v_mfma_f32_16x16x32_bf16 v[44:47], v[122:125], v[170:173], v[44:47]
	v_mfma_f32_16x16x32_bf16 v[40:43], v[130:133], v[170:173], v[40:43]
	v_mfma_f32_16x16x32_bf16 v[28:31], v[122:125], v[178:181], v[28:31]
	v_mfma_f32_16x16x32_bf16 v[24:27], v[130:133], v[178:181], v[24:27]
	v_mfma_f32_16x16x32_bf16 v[12:15], v[122:125], v[186:189], v[12:15]
	v_mfma_f32_16x16x32_bf16 v[8:11], v[130:133], v[186:189], v[8:11]
	v_mfma_f32_16x16x32_bf16 v[60:63], v[126:129], v[166:169], v[60:63]
	v_mfma_f32_16x16x32_bf16 v[56:59], v[134:137], v[166:169], v[56:59]
	v_mfma_f32_16x16x32_bf16 v[44:47], v[126:129], v[174:177], v[44:47]
	v_mfma_f32_16x16x32_bf16 v[40:43], v[134:137], v[174:177], v[40:43]
	v_mfma_f32_16x16x32_bf16 v[28:31], v[126:129], v[182:185], v[28:31]
	v_mfma_f32_16x16x32_bf16 v[24:27], v[134:137], v[182:185], v[24:27]
	v_mfma_f32_16x16x32_bf16 v[12:15], v[126:129], v[208:211], v[12:15]
	v_mfma_f32_16x16x32_bf16 v[8:11], v[134:137], v[208:211], v[8:11]
	s_setprio 0
	s_setprio 1
	v_mfma_f32_16x16x32_bf16 v[52:55], v[138:141], v[162:165], v[52:55]
	v_mfma_f32_16x16x32_bf16 v[48:51], v[146:149], v[162:165], v[48:51]
	v_mfma_f32_16x16x32_bf16 v[36:39], v[138:141], v[170:173], v[36:39]
	v_mfma_f32_16x16x32_bf16 v[32:35], v[146:149], v[170:173], v[32:35]
	v_mfma_f32_16x16x32_bf16 v[20:23], v[138:141], v[178:181], v[20:23]
	v_mfma_f32_16x16x32_bf16 v[16:19], v[146:149], v[178:181], v[16:19]
	v_mfma_f32_16x16x32_bf16 v[4:7], v[138:141], v[186:189], v[4:7]
	v_mfma_f32_16x16x32_bf16 v[0:3], v[146:149], v[186:189], v[0:3]
	v_mfma_f32_16x16x32_bf16 v[52:55], v[142:145], v[166:169], v[52:55]
	v_mfma_f32_16x16x32_bf16 v[48:51], v[150:153], v[166:169], v[48:51]
	v_mfma_f32_16x16x32_bf16 v[36:39], v[142:145], v[174:177], v[36:39]
	v_mfma_f32_16x16x32_bf16 v[32:35], v[150:153], v[174:177], v[32:35]
	v_mfma_f32_16x16x32_bf16 v[20:23], v[142:145], v[182:185], v[20:23]
	v_mfma_f32_16x16x32_bf16 v[16:19], v[150:153], v[182:185], v[16:19]
	v_mfma_f32_16x16x32_bf16 v[4:7], v[142:145], v[208:211], v[4:7]
	v_mfma_f32_16x16x32_bf16 v[0:3], v[150:153], v[208:211], v[0:3]
	s_setprio 0
	s_barrier
	s_add_i32 s52, 0, 0x18000
	s_add_i32 s53, 0, 0x1c000
	v_add_u32_e32 v134, s52, v245
	v_add_u32_e32 v150, s53, v245
	ds_read_b128 v[122:125], v134
	ds_read_b128 v[126:129], v134 offset:1024
	ds_read_b128 v[130:133], v134 offset:2048
	ds_read_b128 v[134:137], v134 offset:3072
	ds_read_b128 v[138:141], v150
	ds_read_b128 v[142:145], v150 offset:1024
	ds_read_b128 v[146:149], v150 offset:2048
	ds_read_b128 v[150:153], v150 offset:3072
	s_add_u32 s30, s30, 0x40000
	s_addc_u32 s31, s31, 0
	s_mov_b32 m0, s42
	v_lshl_add_u64 v[214:215], s[30:31], 0, v[190:191]
	ds_read_b128 v[162:165], v199 offset:32768
	ds_read_b128 v[166:169], v199 offset:33792
	ds_read_b128 v[170:173], v199 offset:34816
	ds_read_b128 v[174:177], v199 offset:35840
	ds_read_b128 v[178:181], v199 offset:36864
	ds_read_b128 v[182:185], v199 offset:37888
	ds_read_b128 v[186:189], v199 offset:38912
	ds_read_b128 v[208:211], v199 offset:39936
	global_load_lds_dwordx4 v[214:215], off
	v_lshl_add_u64 v[214:215], s[30:31], 0, v[192:193]
	s_mov_b32 m0, s43
	s_nop 0
	global_load_lds_dwordx4 v[214:215], off
	s_waitcnt vmcnt(8)
	s_waitcnt lgkmcnt(0)
	s_barrier
	s_setprio 1
	s_waitcnt lgkmcnt(0)
	v_mfma_f32_16x16x32_bf16 v[158:161], v[122:125], v[162:165], v[158:161]
	v_mfma_f32_16x16x32_bf16 v[154:157], v[130:133], v[162:165], v[154:157]
	v_mfma_f32_16x16x32_bf16 v[110:113], v[122:125], v[170:173], v[110:113]
	v_mfma_f32_16x16x32_bf16 v[106:109], v[130:133], v[170:173], v[106:109]
	v_mfma_f32_16x16x32_bf16 v[92:95], v[122:125], v[178:181], v[92:95]
	v_mfma_f32_16x16x32_bf16 v[88:91], v[130:133], v[178:181], v[88:91]
	v_mfma_f32_16x16x32_bf16 v[76:79], v[122:125], v[186:189], v[76:79]
	v_mfma_f32_16x16x32_bf16 v[72:75], v[130:133], v[186:189], v[72:75]
	v_mfma_f32_16x16x32_bf16 v[158:161], v[126:129], v[166:169], v[158:161]
	v_mfma_f32_16x16x32_bf16 v[154:157], v[134:137], v[166:169], v[154:157]
	v_mfma_f32_16x16x32_bf16 v[110:113], v[126:129], v[174:177], v[110:113]
	v_mfma_f32_16x16x32_bf16 v[106:109], v[134:137], v[174:177], v[106:109]
	v_mfma_f32_16x16x32_bf16 v[92:95], v[126:129], v[182:185], v[92:95]
	v_mfma_f32_16x16x32_bf16 v[88:91], v[134:137], v[182:185], v[88:91]
	v_mfma_f32_16x16x32_bf16 v[76:79], v[126:129], v[208:211], v[76:79]
	v_mfma_f32_16x16x32_bf16 v[72:75], v[134:137], v[208:211], v[72:75]
	s_setprio 0
	s_setprio 1
	v_mfma_f32_16x16x32_bf16 v[118:121], v[138:141], v[162:165], v[118:121]
	v_mfma_f32_16x16x32_bf16 v[114:117], v[146:149], v[162:165], v[114:117]
	v_mfma_f32_16x16x32_bf16 v[102:105], v[138:141], v[170:173], v[102:105]
	v_mfma_f32_16x16x32_bf16 v[98:101], v[146:149], v[170:173], v[98:101]
	v_mfma_f32_16x16x32_bf16 v[84:87], v[138:141], v[178:181], v[84:87]
	v_mfma_f32_16x16x32_bf16 v[80:83], v[146:149], v[178:181], v[80:83]
	v_mfma_f32_16x16x32_bf16 v[68:71], v[138:141], v[186:189], v[68:71]
	v_mfma_f32_16x16x32_bf16 v[64:67], v[146:149], v[186:189], v[64:67]
	v_mfma_f32_16x16x32_bf16 v[118:121], v[142:145], v[166:169], v[118:121]
	v_mfma_f32_16x16x32_bf16 v[114:117], v[150:153], v[166:169], v[114:117]
	v_mfma_f32_16x16x32_bf16 v[102:105], v[142:145], v[174:177], v[102:105]
	v_mfma_f32_16x16x32_bf16 v[98:101], v[150:153], v[174:177], v[98:101]
	v_mfma_f32_16x16x32_bf16 v[84:87], v[142:145], v[182:185], v[84:87]
	v_mfma_f32_16x16x32_bf16 v[80:83], v[150:153], v[182:185], v[80:83]
	v_mfma_f32_16x16x32_bf16 v[68:71], v[142:145], v[208:211], v[68:71]
	v_mfma_f32_16x16x32_bf16 v[64:67], v[150:153], v[208:211], v[64:67]
	s_setprio 0
	s_barrier
	s_add_i32 s30, s52, s39
	v_lshl_add_u64 v[194:195], v[194:195], 0, s[64:65]
	s_mov_b32 m0, s30
	ds_read_b128 v[162:165], v199 offset:49152
	ds_read_b128 v[166:169], v199 offset:50176
	ds_read_b128 v[170:173], v199 offset:51200
	ds_read_b128 v[174:177], v199 offset:52224
	ds_read_b128 v[178:181], v199 offset:53248
	ds_read_b128 v[182:185], v199 offset:54272
	ds_read_b128 v[186:189], v199 offset:55296
	ds_read_b128 v[208:211], v199 offset:56320
	global_load_lds_dwordx4 v[194:195], off
	s_add_i32 m0, s30, 0x2000
	s_add_u32 s28, s28, 0x40080
	v_lshl_add_u64 v[194:195], v[196:197], 0, s[64:65]
	s_addc_u32 s29, s29, 0
	s_add_i32 s30, s53, s39
	global_load_lds_dwordx4 v[194:195], off
	v_lshl_add_u64 v[194:195], s[28:29], 0, v[96:97]
	s_mov_b32 m0, s30
	s_nop 0
	global_load_lds_dwordx4 v[194:195], off
	v_lshl_add_u64 v[194:195], s[28:29], 0, v[202:203]
	s_add_i32 m0, s30, 0x2000
	s_nop 0
	global_load_lds_dwordx4 v[194:195], off
	v_lshl_add_u64 v[194:195], v[200:201], 0, s[64:65]
	s_mov_b32 m0, s45
	s_nop 0
	global_load_lds_dwordx4 v[194:195], off
	v_lshl_add_u64 v[194:195], v[212:213], 0, s[64:65]
	s_mov_b32 m0, s46
	s_nop 0
	global_load_lds_dwordx4 v[194:195], off
	s_waitcnt vmcnt(8)
	s_waitcnt lgkmcnt(0)
	s_barrier
	s_setprio 1
	s_waitcnt lgkmcnt(0)
	v_mfma_f32_16x16x32_bf16 v[60:63], v[122:125], v[162:165], v[60:63]
	v_mfma_f32_16x16x32_bf16 v[56:59], v[130:133], v[162:165], v[56:59]
	v_mfma_f32_16x16x32_bf16 v[44:47], v[122:125], v[170:173], v[44:47]
	v_mfma_f32_16x16x32_bf16 v[40:43], v[130:133], v[170:173], v[40:43]
	v_mfma_f32_16x16x32_bf16 v[28:31], v[122:125], v[178:181], v[28:31]
	v_mfma_f32_16x16x32_bf16 v[24:27], v[130:133], v[178:181], v[24:27]
	v_mfma_f32_16x16x32_bf16 v[12:15], v[122:125], v[186:189], v[12:15]
	v_mfma_f32_16x16x32_bf16 v[8:11], v[130:133], v[186:189], v[8:11]
	v_mfma_f32_16x16x32_bf16 v[60:63], v[126:129], v[166:169], v[60:63]
	v_mfma_f32_16x16x32_bf16 v[56:59], v[134:137], v[166:169], v[56:59]
	v_mfma_f32_16x16x32_bf16 v[44:47], v[126:129], v[174:177], v[44:47]
	v_mfma_f32_16x16x32_bf16 v[40:43], v[134:137], v[174:177], v[40:43]
	v_mfma_f32_16x16x32_bf16 v[28:31], v[126:129], v[182:185], v[28:31]
	v_mfma_f32_16x16x32_bf16 v[24:27], v[134:137], v[182:185], v[24:27]
	v_mfma_f32_16x16x32_bf16 v[12:15], v[126:129], v[208:211], v[12:15]
	v_mfma_f32_16x16x32_bf16 v[8:11], v[134:137], v[208:211], v[8:11]
	s_setprio 0
	s_setprio 1
	v_mfma_f32_16x16x32_bf16 v[52:55], v[138:141], v[162:165], v[52:55]
	v_mfma_f32_16x16x32_bf16 v[48:51], v[146:149], v[162:165], v[48:51]
	v_mfma_f32_16x16x32_bf16 v[36:39], v[138:141], v[170:173], v[36:39]
	v_mfma_f32_16x16x32_bf16 v[32:35], v[146:149], v[170:173], v[32:35]
	v_mfma_f32_16x16x32_bf16 v[20:23], v[138:141], v[178:181], v[20:23]
	v_mfma_f32_16x16x32_bf16 v[16:19], v[146:149], v[178:181], v[16:19]
	v_mfma_f32_16x16x32_bf16 v[4:7], v[138:141], v[186:189], v[4:7]
	v_mfma_f32_16x16x32_bf16 v[0:3], v[146:149], v[186:189], v[0:3]
	v_mfma_f32_16x16x32_bf16 v[52:55], v[142:145], v[166:169], v[52:55]
	v_mfma_f32_16x16x32_bf16 v[48:51], v[150:153], v[166:169], v[48:51]
	v_mfma_f32_16x16x32_bf16 v[36:39], v[142:145], v[174:177], v[36:39]
	v_mfma_f32_16x16x32_bf16 v[32:35], v[150:153], v[174:177], v[32:35]
	v_mfma_f32_16x16x32_bf16 v[20:23], v[142:145], v[182:185], v[20:23]
	v_mfma_f32_16x16x32_bf16 v[16:19], v[150:153], v[182:185], v[16:19]
	v_mfma_f32_16x16x32_bf16 v[4:7], v[142:145], v[208:211], v[4:7]
	v_mfma_f32_16x16x32_bf16 v[0:3], v[150:153], v[208:211], v[0:3]
	s_setprio 0
	s_add_i32 s51, s51, 2
	s_add_u32 s26, s26, 0x100
	s_addc_u32 s27, s27, 0
	s_add_u32 s49, s49, 0x100
	s_addc_u32 s50, s50, 0
	s_cmp_gt_u32 s51, 13
	s_barrier
	s_cbranch_scc0 .LBB0_1237
	s_and_b64 vcc, exec, s[12:13]
	s_cbranch_vccz .LBB0_1240
	s_barrier
